# hipcc scanner loop body of the RWKV scan hand-scheduled: 43 instr per step, interleaved reduction chains, no exec juggling
# speedup vs baseline: 1.0059x; 1.0059x over previous
; #define LAS __attribute__((address_space(3)))
; __device__ __forceinline__ void rwkv_scan_phase(Frame& F, const bf16* RKV, const float* WAG, const bf16* AGB, const float* k_k, const float* k_a, const float* r_k, bf16* Y, float* BS, float* ST2) {
;     ...
;             for (int ci = 0; ci < SEQ / SC_T; ++ci) {
;                 const LAS unsigned char* bp = F.lds + (ci & 1) * SC_BUF; LAS float* yb = (LAS float*)(F.lds + SC_YOFF + (ci & 1) * SC_YB);
;     ...
;                 f32x2 r0[4], w0[4], k0[4], a0[4], b0[4], r1[4], w1[4], k1[4], a1[4], b1[4]; float v0, v1;
;                 SC_LOAD(r0, w0, k0, a0, b0, v0, 0);
; #pragma unroll
;                 for (int t = 0; t < SC_T; t += 2) {
;                     SC_LOAD(r1, w1, k1, a1, b1, v1, t + 1);
;                     SC_STEP(r0, w0, k0, a0, b0, v0, t);
;                     if (t + 2 < SC_T) SC_LOAD(r0, w0, k0, a0, b0, v0, t + 2);
;                     SC_STEP(r1, w1, k1, a1, b1, v1, t + 1);
;                 }
.LBB0_1692:
	s_and_b32 s6, s0, 1
	s_mul_i32 s7, s6, 0xb000
	s_lshl_b32 s6, s6, 12
	v_add_u32_e32 v74, s7, v91
	v_add_u32_e32 v75, s7, v103
	v_mbcnt_lo_u32_b32 v77, -1, 0
	v_mbcnt_hi_u32_b32 v77, -1, v77
	v_lshlrev_b32_e32 v77, 2, v77
	v_add_u32_e32 v77, 0x18000, v77
	v_cndmask_b32_e64 v76, v77, v170, s[4:5]
	v_add_u32_e32 v76, s6, v76
	ds_read_b128 v[52:55], v74 offset:24576
	ds_read_b128 v[56:59], v74 offset:24592
	ds_read_b128 v[36:39], v74 offset:8192
	ds_read_b128 v[40:43], v74 offset:8208
	ds_read_b128 v[44:47], v74 offset:16384
	ds_read_b128 v[48:51], v74 offset:16400
	ds_read_b128 v[60:63], v74 offset:32768
	ds_read_b128 v[64:67], v74 offset:32784
	ds_read_b128 v[28:31], v74 offset:0
	ds_read_b128 v[32:35], v74 offset:16
	ds_read_b32 v68, v75 offset:40960
	ds_read_b128 v[130:133], v74 offset:24832
	ds_read_b128 v[134:137], v74 offset:24848
	ds_read_b128 v[114:117], v74 offset:8448
	ds_read_b128 v[118:121], v74 offset:8464
	ds_read_b128 v[122:125], v74 offset:16640
	ds_read_b128 v[126:129], v74 offset:16656
	ds_read_b128 v[138:141], v74 offset:33024
	ds_read_b128 v[142:145], v74 offset:33040
	ds_read_b128 v[106:109], v74 offset:256
	ds_read_b128 v[110:113], v74 offset:272
	ds_read_b32 v72, v75 offset:41088
	s_waitcnt lgkmcnt(11)
	v_pk_mul_f32 v[0:1], v[8:9], v[52:53]
	v_pk_mul_f32 v[2:3], v[10:11], v[54:55]
	v_pk_fma_f32 v[0:1], v[20:21], v[56:57], v[0:1]
	v_pk_fma_f32 v[2:3], v[22:23], v[58:59], v[2:3]
	v_pk_mul_f32 v[12:13], v[8:9], v[36:37]
	v_pk_add_f32 v[0:1], v[0:1], v[2:3]
	v_pk_mul_f32 v[14:15], v[10:11], v[38:39]
	v_pk_mul_f32 v[16:17], v[20:21], v[40:41]
	v_add_f32_e32 v24, v0, v1
	v_pk_mul_f32 v[18:19], v[22:23], v[42:43]
	v_pk_fma_f32 v[12:13], v[44:45], v[68:69], v[12:13] op_sel_hi:[1,0,1]
	v_add_f32_dpp v24, v24, v24 quad_perm:[1,0,3,2] row_mask:0xf bank_mask:0xf bound_ctrl:1
	v_pk_fma_f32 v[14:15], v[46:47], v[68:69], v[14:15] op_sel_hi:[1,0,1]
	v_pk_fma_f32 v[16:17], v[48:49], v[68:69], v[16:17] op_sel_hi:[1,0,1]
	v_add_f32_dpp v24, v24, v24 quad_perm:[2,3,0,1] row_mask:0xf bank_mask:0xf bound_ctrl:1
	v_pk_fma_f32 v[18:19], v[50:51], v[68:69], v[18:19] op_sel_hi:[1,0,1]
	s_nop 0
	v_add_f32_dpp v24, v24, v24 row_half_mirror row_mask:0xf bank_mask:0xf bound_ctrl:1
	v_pk_fma_f32 v[8:9], v[60:61], v[24:25], v[12:13] op_sel_hi:[1,0,1]
	v_pk_fma_f32 v[10:11], v[62:63], v[24:25], v[14:15] op_sel_hi:[1,0,1]
	v_pk_fma_f32 v[20:21], v[64:65], v[24:25], v[16:17] op_sel_hi:[1,0,1]
	v_pk_fma_f32 v[22:23], v[66:67], v[24:25], v[18:19] op_sel_hi:[1,0,1]
	v_pk_mul_f32 v[4:5], v[8:9], v[28:29]
	v_pk_mul_f32 v[6:7], v[10:11], v[30:31]
	v_pk_fma_f32 v[4:5], v[20:21], v[32:33], v[4:5]
	v_pk_fma_f32 v[6:7], v[22:23], v[34:35], v[6:7]
	ds_read_b128 v[52:55], v74 offset:25088
	ds_read_b128 v[56:59], v74 offset:25104
	ds_read_b128 v[36:39], v74 offset:8704
	ds_read_b128 v[40:43], v74 offset:8720
	ds_read_b128 v[44:47], v74 offset:16896
	ds_read_b128 v[48:51], v74 offset:16912
	ds_read_b128 v[60:63], v74 offset:33280
	ds_read_b128 v[64:67], v74 offset:33296
	ds_read_b128 v[28:31], v74 offset:512
	ds_read_b128 v[32:35], v74 offset:528
	ds_read_b32 v68, v75 offset:41216
	s_waitcnt lgkmcnt(11)
	v_pk_mul_f32 v[0:1], v[8:9], v[130:131]
	v_pk_mul_f32 v[2:3], v[10:11], v[132:133]
	v_pk_fma_f32 v[0:1], v[20:21], v[134:135], v[0:1]
	v_pk_fma_f32 v[2:3], v[22:23], v[136:137], v[2:3]
	v_pk_add_f32 v[4:5], v[4:5], v[6:7]
	v_pk_mul_f32 v[12:13], v[8:9], v[114:115]
	v_pk_add_f32 v[0:1], v[0:1], v[2:3]
	v_pk_mul_f32 v[14:15], v[10:11], v[116:117]
	v_add_f32_e32 v26, v4, v5
	v_pk_mul_f32 v[16:17], v[20:21], v[118:119]
	v_add_f32_e32 v24, v0, v1
	v_pk_mul_f32 v[18:19], v[22:23], v[120:121]
	v_pk_fma_f32 v[12:13], v[122:123], v[72:73], v[12:13] op_sel_hi:[1,0,1]
	v_add_f32_dpp v26, v26, v26 quad_perm:[1,0,3,2] row_mask:0xf bank_mask:0xf bound_ctrl:1
	v_add_f32_dpp v24, v24, v24 quad_perm:[1,0,3,2] row_mask:0xf bank_mask:0xf bound_ctrl:1
	v_pk_fma_f32 v[14:15], v[124:125], v[72:73], v[14:15] op_sel_hi:[1,0,1]
	v_pk_fma_f32 v[16:17], v[126:127], v[72:73], v[16:17] op_sel_hi:[1,0,1]
	v_add_f32_dpp v26, v26, v26 quad_perm:[2,3,0,1] row_mask:0xf bank_mask:0xf bound_ctrl:1
	v_add_f32_dpp v24, v24, v24 quad_perm:[2,3,0,1] row_mask:0xf bank_mask:0xf bound_ctrl:1
	v_pk_fma_f32 v[18:19], v[128:129], v[72:73], v[18:19] op_sel_hi:[1,0,1]
	v_add_f32_dpp v26, v26, v26 row_half_mirror row_mask:0xf bank_mask:0xf bound_ctrl:1
	v_add_f32_dpp v24, v24, v24 row_half_mirror row_mask:0xf bank_mask:0xf bound_ctrl:1
	ds_write_b32 v76, v26 offset:0
	v_pk_fma_f32 v[8:9], v[138:139], v[24:25], v[12:13] op_sel_hi:[1,0,1]
	v_pk_fma_f32 v[10:11], v[140:141], v[24:25], v[14:15] op_sel_hi:[1,0,1]
	v_pk_fma_f32 v[20:21], v[142:143], v[24:25], v[16:17] op_sel_hi:[1,0,1]
	v_pk_fma_f32 v[22:23], v[144:145], v[24:25], v[18:19] op_sel_hi:[1,0,1]
	v_pk_mul_f32 v[4:5], v[8:9], v[106:107]
	v_pk_mul_f32 v[6:7], v[10:11], v[108:109]
	v_pk_fma_f32 v[4:5], v[20:21], v[110:111], v[4:5]
	v_pk_fma_f32 v[6:7], v[22:23], v[112:113], v[6:7]
	ds_read_b128 v[130:133], v74 offset:25344
	ds_read_b128 v[134:137], v74 offset:25360
	ds_read_b128 v[114:117], v74 offset:8960
	ds_read_b128 v[118:121], v74 offset:8976
	ds_read_b128 v[122:125], v74 offset:17152
	ds_read_b128 v[126:129], v74 offset:17168
	ds_read_b128 v[138:141], v74 offset:33536
	ds_read_b128 v[142:145], v74 offset:33552
	ds_read_b128 v[106:109], v74 offset:768
	ds_read_b128 v[110:113], v74 offset:784
	ds_read_b32 v72, v75 offset:41344
	s_waitcnt lgkmcnt(12)
; __device__ __forceinline__ void rwkv_scan_phase(Frame& F, const bf16* RKV, const float* WAG, const bf16* AGB, const float* k_k, const float* k_a, const float* r_k, bf16* Y, float* BS, float* ST2) {
;     ...
;                 f32x2 r0[4], w0[4], k0[4], a0[4], b0[4], r1[4], w1[4], k1[4], a1[4], b1[4]; float v0, v1;
;                 SC_LOAD(r0, w0, k0, a0, b0, v0, 0);
; #pragma unroll
;                 for (int t = 0; t < SC_T; t += 2) {
;                     SC_LOAD(r1, w1, k1, a1, b1, v1, t + 1);
;                     SC_STEP(r0, w0, k0, a0, b0, v0, t);
;                     if (t + 2 < SC_T) SC_LOAD(r0, w0, k0, a0, b0, v0, t + 2);
;                     SC_STEP(r1, w1, k1, a1, b1, v1, t + 1);
;                 }
	v_pk_mul_f32 v[0:1], v[8:9], v[52:53]
	v_pk_mul_f32 v[2:3], v[10:11], v[54:55]
	v_pk_fma_f32 v[0:1], v[20:21], v[56:57], v[0:1]
	v_pk_fma_f32 v[2:3], v[22:23], v[58:59], v[2:3]
	v_pk_add_f32 v[4:5], v[4:5], v[6:7]
	v_pk_mul_f32 v[12:13], v[8:9], v[36:37]
	v_pk_add_f32 v[0:1], v[0:1], v[2:3]
	v_pk_mul_f32 v[14:15], v[10:11], v[38:39]
	v_add_f32_e32 v26, v4, v5
	v_pk_mul_f32 v[16:17], v[20:21], v[40:41]
	v_add_f32_e32 v24, v0, v1
	v_pk_mul_f32 v[18:19], v[22:23], v[42:43]
	v_pk_fma_f32 v[12:13], v[44:45], v[68:69], v[12:13] op_sel_hi:[1,0,1]
	v_add_f32_dpp v26, v26, v26 quad_perm:[1,0,3,2] row_mask:0xf bank_mask:0xf bound_ctrl:1
	v_add_f32_dpp v24, v24, v24 quad_perm:[1,0,3,2] row_mask:0xf bank_mask:0xf bound_ctrl:1
	v_pk_fma_f32 v[14:15], v[46:47], v[68:69], v[14:15] op_sel_hi:[1,0,1]
	v_pk_fma_f32 v[16:17], v[48:49], v[68:69], v[16:17] op_sel_hi:[1,0,1]
	v_add_f32_dpp v26, v26, v26 quad_perm:[2,3,0,1] row_mask:0xf bank_mask:0xf bound_ctrl:1
	v_add_f32_dpp v24, v24, v24 quad_perm:[2,3,0,1] row_mask:0xf bank_mask:0xf bound_ctrl:1
	v_pk_fma_f32 v[18:19], v[50:51], v[68:69], v[18:19] op_sel_hi:[1,0,1]
	v_add_f32_dpp v26, v26, v26 row_half_mirror row_mask:0xf bank_mask:0xf bound_ctrl:1
	v_add_f32_dpp v24, v24, v24 row_half_mirror row_mask:0xf bank_mask:0xf bound_ctrl:1
	ds_write_b32 v76, v26 offset:128
	v_pk_fma_f32 v[8:9], v[60:61], v[24:25], v[12:13] op_sel_hi:[1,0,1]
	v_pk_fma_f32 v[10:11], v[62:63], v[24:25], v[14:15] op_sel_hi:[1,0,1]
	v_pk_fma_f32 v[20:21], v[64:65], v[24:25], v[16:17] op_sel_hi:[1,0,1]
	v_pk_fma_f32 v[22:23], v[66:67], v[24:25], v[18:19] op_sel_hi:[1,0,1]
	v_pk_mul_f32 v[4:5], v[8:9], v[28:29]
	v_pk_mul_f32 v[6:7], v[10:11], v[30:31]
	v_pk_fma_f32 v[4:5], v[20:21], v[32:33], v[4:5]
	v_pk_fma_f32 v[6:7], v[22:23], v[34:35], v[6:7]
	ds_read_b128 v[52:55], v74 offset:25600
	ds_read_b128 v[56:59], v74 offset:25616
	ds_read_b128 v[36:39], v74 offset:9216
	ds_read_b128 v[40:43], v74 offset:9232
	ds_read_b128 v[44:47], v74 offset:17408
	ds_read_b128 v[48:51], v74 offset:17424
	ds_read_b128 v[60:63], v74 offset:33792
	ds_read_b128 v[64:67], v74 offset:33808
	ds_read_b128 v[28:31], v74 offset:1024
	ds_read_b128 v[32:35], v74 offset:1040
	ds_read_b32 v68, v75 offset:41472
	s_waitcnt lgkmcnt(12)
	v_pk_mul_f32 v[0:1], v[8:9], v[130:131]
	v_pk_mul_f32 v[2:3], v[10:11], v[132:133]
	v_pk_fma_f32 v[0:1], v[20:21], v[134:135], v[0:1]
	v_pk_fma_f32 v[2:3], v[22:23], v[136:137], v[2:3]
	v_pk_add_f32 v[4:5], v[4:5], v[6:7]
	v_pk_mul_f32 v[12:13], v[8:9], v[114:115]
	v_pk_add_f32 v[0:1], v[0:1], v[2:3]
	v_pk_mul_f32 v[14:15], v[10:11], v[116:117]
	v_add_f32_e32 v26, v4, v5
	v_pk_mul_f32 v[16:17], v[20:21], v[118:119]
	v_add_f32_e32 v24, v0, v1
	v_pk_mul_f32 v[18:19], v[22:23], v[120:121]
	v_pk_fma_f32 v[12:13], v[122:123], v[72:73], v[12:13] op_sel_hi:[1,0,1]
	v_add_f32_dpp v26, v26, v26 quad_perm:[1,0,3,2] row_mask:0xf bank_mask:0xf bound_ctrl:1
	v_add_f32_dpp v24, v24, v24 quad_perm:[1,0,3,2] row_mask:0xf bank_mask:0xf bound_ctrl:1
	v_pk_fma_f32 v[14:15], v[124:125], v[72:73], v[14:15] op_sel_hi:[1,0,1]
	v_pk_fma_f32 v[16:17], v[126:127], v[72:73], v[16:17] op_sel_hi:[1,0,1]
	v_add_f32_dpp v26, v26, v26 quad_perm:[2,3,0,1] row_mask:0xf bank_mask:0xf bound_ctrl:1
	v_add_f32_dpp v24, v24, v24 quad_perm:[2,3,0,1] row_mask:0xf bank_mask:0xf bound_ctrl:1
	v_pk_fma_f32 v[18:19], v[128:129], v[72:73], v[18:19] op_sel_hi:[1,0,1]
	v_add_f32_dpp v26, v26, v26 row_half_mirror row_mask:0xf bank_mask:0xf bound_ctrl:1
	v_add_f32_dpp v24, v24, v24 row_half_mirror row_mask:0xf bank_mask:0xf bound_ctrl:1
	ds_write_b32 v76, v26 offset:256
	v_pk_fma_f32 v[8:9], v[138:139], v[24:25], v[12:13] op_sel_hi:[1,0,1]
	v_pk_fma_f32 v[10:11], v[140:141], v[24:25], v[14:15] op_sel_hi:[1,0,1]
	v_pk_fma_f32 v[20:21], v[142:143], v[24:25], v[16:17] op_sel_hi:[1,0,1]
	v_pk_fma_f32 v[22:23], v[144:145], v[24:25], v[18:19] op_sel_hi:[1,0,1]
	v_pk_mul_f32 v[4:5], v[8:9], v[106:107]
	v_pk_mul_f32 v[6:7], v[10:11], v[108:109]
	v_pk_fma_f32 v[4:5], v[20:21], v[110:111], v[4:5]
	v_pk_fma_f32 v[6:7], v[22:23], v[112:113], v[6:7]
	ds_read_b128 v[130:133], v74 offset:25856
	ds_read_b128 v[134:137], v74 offset:25872
	ds_read_b128 v[114:117], v74 offset:9472
	ds_read_b128 v[118:121], v74 offset:9488
	ds_read_b128 v[122:125], v74 offset:17664
	ds_read_b128 v[126:129], v74 offset:17680
	ds_read_b128 v[138:141], v74 offset:34048
	ds_read_b128 v[142:145], v74 offset:34064
	ds_read_b128 v[106:109], v74 offset:1280
	ds_read_b128 v[110:113], v74 offset:1296
	ds_read_b32 v72, v75 offset:41600
	s_waitcnt lgkmcnt(12)
; __device__ __forceinline__ void rwkv_scan_phase(Frame& F, const bf16* RKV, const float* WAG, const bf16* AGB, const float* k_k, const float* k_a, const float* r_k, bf16* Y, float* BS, float* ST2) {
;     ...
;                 f32x2 r0[4], w0[4], k0[4], a0[4], b0[4], r1[4], w1[4], k1[4], a1[4], b1[4]; float v0, v1;
;                 SC_LOAD(r0, w0, k0, a0, b0, v0, 0);
; #pragma unroll
;                 for (int t = 0; t < SC_T; t += 2) {
;                     SC_LOAD(r1, w1, k1, a1, b1, v1, t + 1);
;                     SC_STEP(r0, w0, k0, a0, b0, v0, t);
;                     if (t + 2 < SC_T) SC_LOAD(r0, w0, k0, a0, b0, v0, t + 2);
;                     SC_STEP(r1, w1, k1, a1, b1, v1, t + 1);
;                 }
	v_pk_mul_f32 v[0:1], v[8:9], v[52:53]
	v_pk_mul_f32 v[2:3], v[10:11], v[54:55]
	v_pk_fma_f32 v[0:1], v[20:21], v[56:57], v[0:1]
	v_pk_fma_f32 v[2:3], v[22:23], v[58:59], v[2:3]
	v_pk_add_f32 v[4:5], v[4:5], v[6:7]
	v_pk_mul_f32 v[12:13], v[8:9], v[36:37]
	v_pk_add_f32 v[0:1], v[0:1], v[2:3]
	v_pk_mul_f32 v[14:15], v[10:11], v[38:39]
	v_add_f32_e32 v26, v4, v5
	v_pk_mul_f32 v[16:17], v[20:21], v[40:41]
	v_add_f32_e32 v24, v0, v1
	v_pk_mul_f32 v[18:19], v[22:23], v[42:43]
	v_pk_fma_f32 v[12:13], v[44:45], v[68:69], v[12:13] op_sel_hi:[1,0,1]
	v_add_f32_dpp v26, v26, v26 quad_perm:[1,0,3,2] row_mask:0xf bank_mask:0xf bound_ctrl:1
	v_add_f32_dpp v24, v24, v24 quad_perm:[1,0,3,2] row_mask:0xf bank_mask:0xf bound_ctrl:1
	v_pk_fma_f32 v[14:15], v[46:47], v[68:69], v[14:15] op_sel_hi:[1,0,1]
	v_pk_fma_f32 v[16:17], v[48:49], v[68:69], v[16:17] op_sel_hi:[1,0,1]
	v_add_f32_dpp v26, v26, v26 quad_perm:[2,3,0,1] row_mask:0xf bank_mask:0xf bound_ctrl:1
	v_add_f32_dpp v24, v24, v24 quad_perm:[2,3,0,1] row_mask:0xf bank_mask:0xf bound_ctrl:1
	v_pk_fma_f32 v[18:19], v[50:51], v[68:69], v[18:19] op_sel_hi:[1,0,1]
	v_add_f32_dpp v26, v26, v26 row_half_mirror row_mask:0xf bank_mask:0xf bound_ctrl:1
	v_add_f32_dpp v24, v24, v24 row_half_mirror row_mask:0xf bank_mask:0xf bound_ctrl:1
	ds_write_b32 v76, v26 offset:384
	v_pk_fma_f32 v[8:9], v[60:61], v[24:25], v[12:13] op_sel_hi:[1,0,1]
	v_pk_fma_f32 v[10:11], v[62:63], v[24:25], v[14:15] op_sel_hi:[1,0,1]
	v_pk_fma_f32 v[20:21], v[64:65], v[24:25], v[16:17] op_sel_hi:[1,0,1]
	v_pk_fma_f32 v[22:23], v[66:67], v[24:25], v[18:19] op_sel_hi:[1,0,1]
	v_pk_mul_f32 v[4:5], v[8:9], v[28:29]
	v_pk_mul_f32 v[6:7], v[10:11], v[30:31]
	v_pk_fma_f32 v[4:5], v[20:21], v[32:33], v[4:5]
	v_pk_fma_f32 v[6:7], v[22:23], v[34:35], v[6:7]
	ds_read_b128 v[52:55], v74 offset:26112
	ds_read_b128 v[56:59], v74 offset:26128
	ds_read_b128 v[36:39], v74 offset:9728
	ds_read_b128 v[40:43], v74 offset:9744
	ds_read_b128 v[44:47], v74 offset:17920
	ds_read_b128 v[48:51], v74 offset:17936
	ds_read_b128 v[60:63], v74 offset:34304
	ds_read_b128 v[64:67], v74 offset:34320
	ds_read_b128 v[28:31], v74 offset:1536
	ds_read_b128 v[32:35], v74 offset:1552
	ds_read_b32 v68, v75 offset:41728
	s_waitcnt lgkmcnt(12)
	v_pk_mul_f32 v[0:1], v[8:9], v[130:131]
	v_pk_mul_f32 v[2:3], v[10:11], v[132:133]
	v_pk_fma_f32 v[0:1], v[20:21], v[134:135], v[0:1]
	v_pk_fma_f32 v[2:3], v[22:23], v[136:137], v[2:3]
	v_pk_add_f32 v[4:5], v[4:5], v[6:7]
	v_pk_mul_f32 v[12:13], v[8:9], v[114:115]
	v_pk_add_f32 v[0:1], v[0:1], v[2:3]
	v_pk_mul_f32 v[14:15], v[10:11], v[116:117]
	v_add_f32_e32 v26, v4, v5
	v_pk_mul_f32 v[16:17], v[20:21], v[118:119]
	v_add_f32_e32 v24, v0, v1
	v_pk_mul_f32 v[18:19], v[22:23], v[120:121]
	v_pk_fma_f32 v[12:13], v[122:123], v[72:73], v[12:13] op_sel_hi:[1,0,1]
	v_add_f32_dpp v26, v26, v26 quad_perm:[1,0,3,2] row_mask:0xf bank_mask:0xf bound_ctrl:1
	v_add_f32_dpp v24, v24, v24 quad_perm:[1,0,3,2] row_mask:0xf bank_mask:0xf bound_ctrl:1
	v_pk_fma_f32 v[14:15], v[124:125], v[72:73], v[14:15] op_sel_hi:[1,0,1]
	v_pk_fma_f32 v[16:17], v[126:127], v[72:73], v[16:17] op_sel_hi:[1,0,1]
	v_add_f32_dpp v26, v26, v26 quad_perm:[2,3,0,1] row_mask:0xf bank_mask:0xf bound_ctrl:1
	v_add_f32_dpp v24, v24, v24 quad_perm:[2,3,0,1] row_mask:0xf bank_mask:0xf bound_ctrl:1
	v_pk_fma_f32 v[18:19], v[128:129], v[72:73], v[18:19] op_sel_hi:[1,0,1]
	v_add_f32_dpp v26, v26, v26 row_half_mirror row_mask:0xf bank_mask:0xf bound_ctrl:1
	v_add_f32_dpp v24, v24, v24 row_half_mirror row_mask:0xf bank_mask:0xf bound_ctrl:1
	ds_write_b32 v76, v26 offset:512
	v_pk_fma_f32 v[8:9], v[138:139], v[24:25], v[12:13] op_sel_hi:[1,0,1]
	v_pk_fma_f32 v[10:11], v[140:141], v[24:25], v[14:15] op_sel_hi:[1,0,1]
	v_pk_fma_f32 v[20:21], v[142:143], v[24:25], v[16:17] op_sel_hi:[1,0,1]
	v_pk_fma_f32 v[22:23], v[144:145], v[24:25], v[18:19] op_sel_hi:[1,0,1]
	v_pk_mul_f32 v[4:5], v[8:9], v[106:107]
	v_pk_mul_f32 v[6:7], v[10:11], v[108:109]
	v_pk_fma_f32 v[4:5], v[20:21], v[110:111], v[4:5]
	v_pk_fma_f32 v[6:7], v[22:23], v[112:113], v[6:7]
	ds_read_b128 v[130:133], v74 offset:26368
	ds_read_b128 v[134:137], v74 offset:26384
	ds_read_b128 v[114:117], v74 offset:9984
	ds_read_b128 v[118:121], v74 offset:10000
	ds_read_b128 v[122:125], v74 offset:18176
	ds_read_b128 v[126:129], v74 offset:18192
	ds_read_b128 v[138:141], v74 offset:34560
	ds_read_b128 v[142:145], v74 offset:34576
	ds_read_b128 v[106:109], v74 offset:1792
	ds_read_b128 v[110:113], v74 offset:1808
	ds_read_b32 v72, v75 offset:41856
	s_waitcnt lgkmcnt(12)
; __device__ __forceinline__ void rwkv_scan_phase(Frame& F, const bf16* RKV, const float* WAG, const bf16* AGB, const float* k_k, const float* k_a, const float* r_k, bf16* Y, float* BS, float* ST2) {
;     ...
;                 f32x2 r0[4], w0[4], k0[4], a0[4], b0[4], r1[4], w1[4], k1[4], a1[4], b1[4]; float v0, v1;
;                 SC_LOAD(r0, w0, k0, a0, b0, v0, 0);
; #pragma unroll
;                 for (int t = 0; t < SC_T; t += 2) {
;                     SC_LOAD(r1, w1, k1, a1, b1, v1, t + 1);
;                     SC_STEP(r0, w0, k0, a0, b0, v0, t);
;                     if (t + 2 < SC_T) SC_LOAD(r0, w0, k0, a0, b0, v0, t + 2);
;                     SC_STEP(r1, w1, k1, a1, b1, v1, t + 1);
;                 }
	v_pk_mul_f32 v[0:1], v[8:9], v[52:53]
	v_pk_mul_f32 v[2:3], v[10:11], v[54:55]
	v_pk_fma_f32 v[0:1], v[20:21], v[56:57], v[0:1]
	v_pk_fma_f32 v[2:3], v[22:23], v[58:59], v[2:3]
	v_pk_add_f32 v[4:5], v[4:5], v[6:7]
	v_pk_mul_f32 v[12:13], v[8:9], v[36:37]
	v_pk_add_f32 v[0:1], v[0:1], v[2:3]
	v_pk_mul_f32 v[14:15], v[10:11], v[38:39]
	v_add_f32_e32 v26, v4, v5
	v_pk_mul_f32 v[16:17], v[20:21], v[40:41]
	v_add_f32_e32 v24, v0, v1
	v_pk_mul_f32 v[18:19], v[22:23], v[42:43]
	v_pk_fma_f32 v[12:13], v[44:45], v[68:69], v[12:13] op_sel_hi:[1,0,1]
	v_add_f32_dpp v26, v26, v26 quad_perm:[1,0,3,2] row_mask:0xf bank_mask:0xf bound_ctrl:1
	v_add_f32_dpp v24, v24, v24 quad_perm:[1,0,3,2] row_mask:0xf bank_mask:0xf bound_ctrl:1
	v_pk_fma_f32 v[14:15], v[46:47], v[68:69], v[14:15] op_sel_hi:[1,0,1]
	v_pk_fma_f32 v[16:17], v[48:49], v[68:69], v[16:17] op_sel_hi:[1,0,1]
	v_add_f32_dpp v26, v26, v26 quad_perm:[2,3,0,1] row_mask:0xf bank_mask:0xf bound_ctrl:1
	v_add_f32_dpp v24, v24, v24 quad_perm:[2,3,0,1] row_mask:0xf bank_mask:0xf bound_ctrl:1
	v_pk_fma_f32 v[18:19], v[50:51], v[68:69], v[18:19] op_sel_hi:[1,0,1]
	v_add_f32_dpp v26, v26, v26 row_half_mirror row_mask:0xf bank_mask:0xf bound_ctrl:1
	v_add_f32_dpp v24, v24, v24 row_half_mirror row_mask:0xf bank_mask:0xf bound_ctrl:1
	ds_write_b32 v76, v26 offset:640
	v_pk_fma_f32 v[8:9], v[60:61], v[24:25], v[12:13] op_sel_hi:[1,0,1]
	v_pk_fma_f32 v[10:11], v[62:63], v[24:25], v[14:15] op_sel_hi:[1,0,1]
	v_pk_fma_f32 v[20:21], v[64:65], v[24:25], v[16:17] op_sel_hi:[1,0,1]
	v_pk_fma_f32 v[22:23], v[66:67], v[24:25], v[18:19] op_sel_hi:[1,0,1]
	v_pk_mul_f32 v[4:5], v[8:9], v[28:29]
	v_pk_mul_f32 v[6:7], v[10:11], v[30:31]
	v_pk_fma_f32 v[4:5], v[20:21], v[32:33], v[4:5]
	v_pk_fma_f32 v[6:7], v[22:23], v[34:35], v[6:7]
	ds_read_b128 v[52:55], v74 offset:26624
	ds_read_b128 v[56:59], v74 offset:26640
	ds_read_b128 v[36:39], v74 offset:10240
	ds_read_b128 v[40:43], v74 offset:10256
	ds_read_b128 v[44:47], v74 offset:18432
	ds_read_b128 v[48:51], v74 offset:18448
	ds_read_b128 v[60:63], v74 offset:34816
	ds_read_b128 v[64:67], v74 offset:34832
	ds_read_b128 v[28:31], v74 offset:2048
	ds_read_b128 v[32:35], v74 offset:2064
	ds_read_b32 v68, v75 offset:41984
	s_waitcnt lgkmcnt(12)
	v_pk_mul_f32 v[0:1], v[8:9], v[130:131]
	v_pk_mul_f32 v[2:3], v[10:11], v[132:133]
	v_pk_fma_f32 v[0:1], v[20:21], v[134:135], v[0:1]
	v_pk_fma_f32 v[2:3], v[22:23], v[136:137], v[2:3]
	v_pk_add_f32 v[4:5], v[4:5], v[6:7]
	v_pk_mul_f32 v[12:13], v[8:9], v[114:115]
	v_pk_add_f32 v[0:1], v[0:1], v[2:3]
	v_pk_mul_f32 v[14:15], v[10:11], v[116:117]
	v_add_f32_e32 v26, v4, v5
	v_pk_mul_f32 v[16:17], v[20:21], v[118:119]
	v_add_f32_e32 v24, v0, v1
	v_pk_mul_f32 v[18:19], v[22:23], v[120:121]
	v_pk_fma_f32 v[12:13], v[122:123], v[72:73], v[12:13] op_sel_hi:[1,0,1]
	v_add_f32_dpp v26, v26, v26 quad_perm:[1,0,3,2] row_mask:0xf bank_mask:0xf bound_ctrl:1
	v_add_f32_dpp v24, v24, v24 quad_perm:[1,0,3,2] row_mask:0xf bank_mask:0xf bound_ctrl:1
	v_pk_fma_f32 v[14:15], v[124:125], v[72:73], v[14:15] op_sel_hi:[1,0,1]
	v_pk_fma_f32 v[16:17], v[126:127], v[72:73], v[16:17] op_sel_hi:[1,0,1]
	v_add_f32_dpp v26, v26, v26 quad_perm:[2,3,0,1] row_mask:0xf bank_mask:0xf bound_ctrl:1
	v_add_f32_dpp v24, v24, v24 quad_perm:[2,3,0,1] row_mask:0xf bank_mask:0xf bound_ctrl:1
	v_pk_fma_f32 v[18:19], v[128:129], v[72:73], v[18:19] op_sel_hi:[1,0,1]
	v_add_f32_dpp v26, v26, v26 row_half_mirror row_mask:0xf bank_mask:0xf bound_ctrl:1
	v_add_f32_dpp v24, v24, v24 row_half_mirror row_mask:0xf bank_mask:0xf bound_ctrl:1
	ds_write_b32 v76, v26 offset:768
	v_pk_fma_f32 v[8:9], v[138:139], v[24:25], v[12:13] op_sel_hi:[1,0,1]
	v_pk_fma_f32 v[10:11], v[140:141], v[24:25], v[14:15] op_sel_hi:[1,0,1]
	v_pk_fma_f32 v[20:21], v[142:143], v[24:25], v[16:17] op_sel_hi:[1,0,1]
	v_pk_fma_f32 v[22:23], v[144:145], v[24:25], v[18:19] op_sel_hi:[1,0,1]
	v_pk_mul_f32 v[4:5], v[8:9], v[106:107]
	v_pk_mul_f32 v[6:7], v[10:11], v[108:109]
	v_pk_fma_f32 v[4:5], v[20:21], v[110:111], v[4:5]
	v_pk_fma_f32 v[6:7], v[22:23], v[112:113], v[6:7]
	ds_read_b128 v[130:133], v74 offset:26880
	ds_read_b128 v[134:137], v74 offset:26896
	ds_read_b128 v[114:117], v74 offset:10496
	ds_read_b128 v[118:121], v74 offset:10512
	ds_read_b128 v[122:125], v74 offset:18688
	ds_read_b128 v[126:129], v74 offset:18704
	ds_read_b128 v[138:141], v74 offset:35072
	ds_read_b128 v[142:145], v74 offset:35088
	ds_read_b128 v[106:109], v74 offset:2304
	ds_read_b128 v[110:113], v74 offset:2320
	ds_read_b32 v72, v75 offset:42112
	s_waitcnt lgkmcnt(12)
; __device__ __forceinline__ void rwkv_scan_phase(Frame& F, const bf16* RKV, const float* WAG, const bf16* AGB, const float* k_k, const float* k_a, const float* r_k, bf16* Y, float* BS, float* ST2) {
;     ...
;                 f32x2 r0[4], w0[4], k0[4], a0[4], b0[4], r1[4], w1[4], k1[4], a1[4], b1[4]; float v0, v1;
;                 SC_LOAD(r0, w0, k0, a0, b0, v0, 0);
; #pragma unroll
;                 for (int t = 0; t < SC_T; t += 2) {
;                     SC_LOAD(r1, w1, k1, a1, b1, v1, t + 1);
;                     SC_STEP(r0, w0, k0, a0, b0, v0, t);
;                     if (t + 2 < SC_T) SC_LOAD(r0, w0, k0, a0, b0, v0, t + 2);
;                     SC_STEP(r1, w1, k1, a1, b1, v1, t + 1);
;                 }
	v_pk_mul_f32 v[0:1], v[8:9], v[52:53]
	v_pk_mul_f32 v[2:3], v[10:11], v[54:55]
	v_pk_fma_f32 v[0:1], v[20:21], v[56:57], v[0:1]
	v_pk_fma_f32 v[2:3], v[22:23], v[58:59], v[2:3]
	v_pk_add_f32 v[4:5], v[4:5], v[6:7]
	v_pk_mul_f32 v[12:13], v[8:9], v[36:37]
	v_pk_add_f32 v[0:1], v[0:1], v[2:3]
	v_pk_mul_f32 v[14:15], v[10:11], v[38:39]
	v_add_f32_e32 v26, v4, v5
	v_pk_mul_f32 v[16:17], v[20:21], v[40:41]
	v_add_f32_e32 v24, v0, v1
	v_pk_mul_f32 v[18:19], v[22:23], v[42:43]
	v_pk_fma_f32 v[12:13], v[44:45], v[68:69], v[12:13] op_sel_hi:[1,0,1]
	v_add_f32_dpp v26, v26, v26 quad_perm:[1,0,3,2] row_mask:0xf bank_mask:0xf bound_ctrl:1
	v_add_f32_dpp v24, v24, v24 quad_perm:[1,0,3,2] row_mask:0xf bank_mask:0xf bound_ctrl:1
	v_pk_fma_f32 v[14:15], v[46:47], v[68:69], v[14:15] op_sel_hi:[1,0,1]
	v_pk_fma_f32 v[16:17], v[48:49], v[68:69], v[16:17] op_sel_hi:[1,0,1]
	v_add_f32_dpp v26, v26, v26 quad_perm:[2,3,0,1] row_mask:0xf bank_mask:0xf bound_ctrl:1
	v_add_f32_dpp v24, v24, v24 quad_perm:[2,3,0,1] row_mask:0xf bank_mask:0xf bound_ctrl:1
	v_pk_fma_f32 v[18:19], v[50:51], v[68:69], v[18:19] op_sel_hi:[1,0,1]
	v_add_f32_dpp v26, v26, v26 row_half_mirror row_mask:0xf bank_mask:0xf bound_ctrl:1
	v_add_f32_dpp v24, v24, v24 row_half_mirror row_mask:0xf bank_mask:0xf bound_ctrl:1
	ds_write_b32 v76, v26 offset:896
	v_pk_fma_f32 v[8:9], v[60:61], v[24:25], v[12:13] op_sel_hi:[1,0,1]
	v_pk_fma_f32 v[10:11], v[62:63], v[24:25], v[14:15] op_sel_hi:[1,0,1]
	v_pk_fma_f32 v[20:21], v[64:65], v[24:25], v[16:17] op_sel_hi:[1,0,1]
	v_pk_fma_f32 v[22:23], v[66:67], v[24:25], v[18:19] op_sel_hi:[1,0,1]
	v_pk_mul_f32 v[4:5], v[8:9], v[28:29]
	v_pk_mul_f32 v[6:7], v[10:11], v[30:31]
	v_pk_fma_f32 v[4:5], v[20:21], v[32:33], v[4:5]
	v_pk_fma_f32 v[6:7], v[22:23], v[34:35], v[6:7]
	ds_read_b128 v[52:55], v74 offset:27136
	ds_read_b128 v[56:59], v74 offset:27152
	ds_read_b128 v[36:39], v74 offset:10752
	ds_read_b128 v[40:43], v74 offset:10768
	ds_read_b128 v[44:47], v74 offset:18944
	ds_read_b128 v[48:51], v74 offset:18960
	ds_read_b128 v[60:63], v74 offset:35328
	ds_read_b128 v[64:67], v74 offset:35344
	ds_read_b128 v[28:31], v74 offset:2560
	ds_read_b128 v[32:35], v74 offset:2576
	ds_read_b32 v68, v75 offset:42240
	s_waitcnt lgkmcnt(12)
	v_pk_mul_f32 v[0:1], v[8:9], v[130:131]
	v_pk_mul_f32 v[2:3], v[10:11], v[132:133]
	v_pk_fma_f32 v[0:1], v[20:21], v[134:135], v[0:1]
	v_pk_fma_f32 v[2:3], v[22:23], v[136:137], v[2:3]
	v_pk_add_f32 v[4:5], v[4:5], v[6:7]
	v_pk_mul_f32 v[12:13], v[8:9], v[114:115]
	v_pk_add_f32 v[0:1], v[0:1], v[2:3]
	v_pk_mul_f32 v[14:15], v[10:11], v[116:117]
	v_add_f32_e32 v26, v4, v5
	v_pk_mul_f32 v[16:17], v[20:21], v[118:119]
	v_add_f32_e32 v24, v0, v1
	v_pk_mul_f32 v[18:19], v[22:23], v[120:121]
	v_pk_fma_f32 v[12:13], v[122:123], v[72:73], v[12:13] op_sel_hi:[1,0,1]
	v_add_f32_dpp v26, v26, v26 quad_perm:[1,0,3,2] row_mask:0xf bank_mask:0xf bound_ctrl:1
	v_add_f32_dpp v24, v24, v24 quad_perm:[1,0,3,2] row_mask:0xf bank_mask:0xf bound_ctrl:1
	v_pk_fma_f32 v[14:15], v[124:125], v[72:73], v[14:15] op_sel_hi:[1,0,1]
	v_pk_fma_f32 v[16:17], v[126:127], v[72:73], v[16:17] op_sel_hi:[1,0,1]
	v_add_f32_dpp v26, v26, v26 quad_perm:[2,3,0,1] row_mask:0xf bank_mask:0xf bound_ctrl:1
	v_add_f32_dpp v24, v24, v24 quad_perm:[2,3,0,1] row_mask:0xf bank_mask:0xf bound_ctrl:1
	v_pk_fma_f32 v[18:19], v[128:129], v[72:73], v[18:19] op_sel_hi:[1,0,1]
	v_add_f32_dpp v26, v26, v26 row_half_mirror row_mask:0xf bank_mask:0xf bound_ctrl:1
	v_add_f32_dpp v24, v24, v24 row_half_mirror row_mask:0xf bank_mask:0xf bound_ctrl:1
	ds_write_b32 v76, v26 offset:1024
	v_pk_fma_f32 v[8:9], v[138:139], v[24:25], v[12:13] op_sel_hi:[1,0,1]
	v_pk_fma_f32 v[10:11], v[140:141], v[24:25], v[14:15] op_sel_hi:[1,0,1]
	v_pk_fma_f32 v[20:21], v[142:143], v[24:25], v[16:17] op_sel_hi:[1,0,1]
	v_pk_fma_f32 v[22:23], v[144:145], v[24:25], v[18:19] op_sel_hi:[1,0,1]
	v_pk_mul_f32 v[4:5], v[8:9], v[106:107]
	v_pk_mul_f32 v[6:7], v[10:11], v[108:109]
	v_pk_fma_f32 v[4:5], v[20:21], v[110:111], v[4:5]
	v_pk_fma_f32 v[6:7], v[22:23], v[112:113], v[6:7]
	ds_read_b128 v[130:133], v74 offset:27392
	ds_read_b128 v[134:137], v74 offset:27408
	ds_read_b128 v[114:117], v74 offset:11008
	ds_read_b128 v[118:121], v74 offset:11024
	ds_read_b128 v[122:125], v74 offset:19200
	ds_read_b128 v[126:129], v74 offset:19216
	ds_read_b128 v[138:141], v74 offset:35584
	ds_read_b128 v[142:145], v74 offset:35600
	ds_read_b128 v[106:109], v74 offset:2816
	ds_read_b128 v[110:113], v74 offset:2832
	ds_read_b32 v72, v75 offset:42368
	s_waitcnt lgkmcnt(12)
; __device__ __forceinline__ void rwkv_scan_phase(Frame& F, const bf16* RKV, const float* WAG, const bf16* AGB, const float* k_k, const float* k_a, const float* r_k, bf16* Y, float* BS, float* ST2) {
;     ...
;                 f32x2 r0[4], w0[4], k0[4], a0[4], b0[4], r1[4], w1[4], k1[4], a1[4], b1[4]; float v0, v1;
;                 SC_LOAD(r0, w0, k0, a0, b0, v0, 0);
; #pragma unroll
;                 for (int t = 0; t < SC_T; t += 2) {
;                     SC_LOAD(r1, w1, k1, a1, b1, v1, t + 1);
;                     SC_STEP(r0, w0, k0, a0, b0, v0, t);
;                     if (t + 2 < SC_T) SC_LOAD(r0, w0, k0, a0, b0, v0, t + 2);
;                     SC_STEP(r1, w1, k1, a1, b1, v1, t + 1);
;                 }
	v_pk_mul_f32 v[0:1], v[8:9], v[52:53]
	v_pk_mul_f32 v[2:3], v[10:11], v[54:55]
	v_pk_fma_f32 v[0:1], v[20:21], v[56:57], v[0:1]
	v_pk_fma_f32 v[2:3], v[22:23], v[58:59], v[2:3]
	v_pk_add_f32 v[4:5], v[4:5], v[6:7]
	v_pk_mul_f32 v[12:13], v[8:9], v[36:37]
	v_pk_add_f32 v[0:1], v[0:1], v[2:3]
	v_pk_mul_f32 v[14:15], v[10:11], v[38:39]
	v_add_f32_e32 v26, v4, v5
	v_pk_mul_f32 v[16:17], v[20:21], v[40:41]
	v_add_f32_e32 v24, v0, v1
	v_pk_mul_f32 v[18:19], v[22:23], v[42:43]
	v_pk_fma_f32 v[12:13], v[44:45], v[68:69], v[12:13] op_sel_hi:[1,0,1]
	v_add_f32_dpp v26, v26, v26 quad_perm:[1,0,3,2] row_mask:0xf bank_mask:0xf bound_ctrl:1
	v_add_f32_dpp v24, v24, v24 quad_perm:[1,0,3,2] row_mask:0xf bank_mask:0xf bound_ctrl:1
	v_pk_fma_f32 v[14:15], v[46:47], v[68:69], v[14:15] op_sel_hi:[1,0,1]
	v_pk_fma_f32 v[16:17], v[48:49], v[68:69], v[16:17] op_sel_hi:[1,0,1]
	v_add_f32_dpp v26, v26, v26 quad_perm:[2,3,0,1] row_mask:0xf bank_mask:0xf bound_ctrl:1
	v_add_f32_dpp v24, v24, v24 quad_perm:[2,3,0,1] row_mask:0xf bank_mask:0xf bound_ctrl:1
	v_pk_fma_f32 v[18:19], v[50:51], v[68:69], v[18:19] op_sel_hi:[1,0,1]
	v_add_f32_dpp v26, v26, v26 row_half_mirror row_mask:0xf bank_mask:0xf bound_ctrl:1
	v_add_f32_dpp v24, v24, v24 row_half_mirror row_mask:0xf bank_mask:0xf bound_ctrl:1
	ds_write_b32 v76, v26 offset:1152
	v_pk_fma_f32 v[8:9], v[60:61], v[24:25], v[12:13] op_sel_hi:[1,0,1]
	v_pk_fma_f32 v[10:11], v[62:63], v[24:25], v[14:15] op_sel_hi:[1,0,1]
	v_pk_fma_f32 v[20:21], v[64:65], v[24:25], v[16:17] op_sel_hi:[1,0,1]
	v_pk_fma_f32 v[22:23], v[66:67], v[24:25], v[18:19] op_sel_hi:[1,0,1]
	v_pk_mul_f32 v[4:5], v[8:9], v[28:29]
	v_pk_mul_f32 v[6:7], v[10:11], v[30:31]
	v_pk_fma_f32 v[4:5], v[20:21], v[32:33], v[4:5]
	v_pk_fma_f32 v[6:7], v[22:23], v[34:35], v[6:7]
	ds_read_b128 v[52:55], v74 offset:27648
	ds_read_b128 v[56:59], v74 offset:27664
	ds_read_b128 v[36:39], v74 offset:11264
	ds_read_b128 v[40:43], v74 offset:11280
	ds_read_b128 v[44:47], v74 offset:19456
	ds_read_b128 v[48:51], v74 offset:19472
	ds_read_b128 v[60:63], v74 offset:35840
	ds_read_b128 v[64:67], v74 offset:35856
	ds_read_b128 v[28:31], v74 offset:3072
	ds_read_b128 v[32:35], v74 offset:3088
	ds_read_b32 v68, v75 offset:42496
	s_waitcnt lgkmcnt(12)
	v_pk_mul_f32 v[0:1], v[8:9], v[130:131]
	v_pk_mul_f32 v[2:3], v[10:11], v[132:133]
	v_pk_fma_f32 v[0:1], v[20:21], v[134:135], v[0:1]
	v_pk_fma_f32 v[2:3], v[22:23], v[136:137], v[2:3]
	v_pk_add_f32 v[4:5], v[4:5], v[6:7]
	v_pk_mul_f32 v[12:13], v[8:9], v[114:115]
	v_pk_add_f32 v[0:1], v[0:1], v[2:3]
	v_pk_mul_f32 v[14:15], v[10:11], v[116:117]
	v_add_f32_e32 v26, v4, v5
	v_pk_mul_f32 v[16:17], v[20:21], v[118:119]
	v_add_f32_e32 v24, v0, v1
	v_pk_mul_f32 v[18:19], v[22:23], v[120:121]
	v_pk_fma_f32 v[12:13], v[122:123], v[72:73], v[12:13] op_sel_hi:[1,0,1]
	v_add_f32_dpp v26, v26, v26 quad_perm:[1,0,3,2] row_mask:0xf bank_mask:0xf bound_ctrl:1
	v_add_f32_dpp v24, v24, v24 quad_perm:[1,0,3,2] row_mask:0xf bank_mask:0xf bound_ctrl:1
	v_pk_fma_f32 v[14:15], v[124:125], v[72:73], v[14:15] op_sel_hi:[1,0,1]
	v_pk_fma_f32 v[16:17], v[126:127], v[72:73], v[16:17] op_sel_hi:[1,0,1]
	v_add_f32_dpp v26, v26, v26 quad_perm:[2,3,0,1] row_mask:0xf bank_mask:0xf bound_ctrl:1
	v_add_f32_dpp v24, v24, v24 quad_perm:[2,3,0,1] row_mask:0xf bank_mask:0xf bound_ctrl:1
	v_pk_fma_f32 v[18:19], v[128:129], v[72:73], v[18:19] op_sel_hi:[1,0,1]
	v_add_f32_dpp v26, v26, v26 row_half_mirror row_mask:0xf bank_mask:0xf bound_ctrl:1
	v_add_f32_dpp v24, v24, v24 row_half_mirror row_mask:0xf bank_mask:0xf bound_ctrl:1
	ds_write_b32 v76, v26 offset:1280
	v_pk_fma_f32 v[8:9], v[138:139], v[24:25], v[12:13] op_sel_hi:[1,0,1]
	v_pk_fma_f32 v[10:11], v[140:141], v[24:25], v[14:15] op_sel_hi:[1,0,1]
	v_pk_fma_f32 v[20:21], v[142:143], v[24:25], v[16:17] op_sel_hi:[1,0,1]
	v_pk_fma_f32 v[22:23], v[144:145], v[24:25], v[18:19] op_sel_hi:[1,0,1]
	v_pk_mul_f32 v[4:5], v[8:9], v[106:107]
	v_pk_mul_f32 v[6:7], v[10:11], v[108:109]
	v_pk_fma_f32 v[4:5], v[20:21], v[110:111], v[4:5]
	v_pk_fma_f32 v[6:7], v[22:23], v[112:113], v[6:7]
	ds_read_b128 v[130:133], v74 offset:27904
	ds_read_b128 v[134:137], v74 offset:27920
	ds_read_b128 v[114:117], v74 offset:11520
	ds_read_b128 v[118:121], v74 offset:11536
	ds_read_b128 v[122:125], v74 offset:19712
	ds_read_b128 v[126:129], v74 offset:19728
	ds_read_b128 v[138:141], v74 offset:36096
	ds_read_b128 v[142:145], v74 offset:36112
	ds_read_b128 v[106:109], v74 offset:3328
	ds_read_b128 v[110:113], v74 offset:3344
	ds_read_b32 v72, v75 offset:42624
	s_waitcnt lgkmcnt(12)
; __device__ __forceinline__ void rwkv_scan_phase(Frame& F, const bf16* RKV, const float* WAG, const bf16* AGB, const float* k_k, const float* k_a, const float* r_k, bf16* Y, float* BS, float* ST2) {
;     ...
;                 f32x2 r0[4], w0[4], k0[4], a0[4], b0[4], r1[4], w1[4], k1[4], a1[4], b1[4]; float v0, v1;
;                 SC_LOAD(r0, w0, k0, a0, b0, v0, 0);
; #pragma unroll
;                 for (int t = 0; t < SC_T; t += 2) {
;                     SC_LOAD(r1, w1, k1, a1, b1, v1, t + 1);
;                     SC_STEP(r0, w0, k0, a0, b0, v0, t);
;                     if (t + 2 < SC_T) SC_LOAD(r0, w0, k0, a0, b0, v0, t + 2);
;                     SC_STEP(r1, w1, k1, a1, b1, v1, t + 1);
;                 }
	v_pk_mul_f32 v[0:1], v[8:9], v[52:53]
	v_pk_mul_f32 v[2:3], v[10:11], v[54:55]
	v_pk_fma_f32 v[0:1], v[20:21], v[56:57], v[0:1]
	v_pk_fma_f32 v[2:3], v[22:23], v[58:59], v[2:3]
	v_pk_add_f32 v[4:5], v[4:5], v[6:7]
	v_pk_mul_f32 v[12:13], v[8:9], v[36:37]
	v_pk_add_f32 v[0:1], v[0:1], v[2:3]
	v_pk_mul_f32 v[14:15], v[10:11], v[38:39]
	v_add_f32_e32 v26, v4, v5
	v_pk_mul_f32 v[16:17], v[20:21], v[40:41]
	v_add_f32_e32 v24, v0, v1
	v_pk_mul_f32 v[18:19], v[22:23], v[42:43]
	v_pk_fma_f32 v[12:13], v[44:45], v[68:69], v[12:13] op_sel_hi:[1,0,1]
	v_add_f32_dpp v26, v26, v26 quad_perm:[1,0,3,2] row_mask:0xf bank_mask:0xf bound_ctrl:1
	v_add_f32_dpp v24, v24, v24 quad_perm:[1,0,3,2] row_mask:0xf bank_mask:0xf bound_ctrl:1
	v_pk_fma_f32 v[14:15], v[46:47], v[68:69], v[14:15] op_sel_hi:[1,0,1]
	v_pk_fma_f32 v[16:17], v[48:49], v[68:69], v[16:17] op_sel_hi:[1,0,1]
	v_add_f32_dpp v26, v26, v26 quad_perm:[2,3,0,1] row_mask:0xf bank_mask:0xf bound_ctrl:1
	v_add_f32_dpp v24, v24, v24 quad_perm:[2,3,0,1] row_mask:0xf bank_mask:0xf bound_ctrl:1
	v_pk_fma_f32 v[18:19], v[50:51], v[68:69], v[18:19] op_sel_hi:[1,0,1]
	v_add_f32_dpp v26, v26, v26 row_half_mirror row_mask:0xf bank_mask:0xf bound_ctrl:1
	v_add_f32_dpp v24, v24, v24 row_half_mirror row_mask:0xf bank_mask:0xf bound_ctrl:1
	ds_write_b32 v76, v26 offset:1408
	v_pk_fma_f32 v[8:9], v[60:61], v[24:25], v[12:13] op_sel_hi:[1,0,1]
	v_pk_fma_f32 v[10:11], v[62:63], v[24:25], v[14:15] op_sel_hi:[1,0,1]
	v_pk_fma_f32 v[20:21], v[64:65], v[24:25], v[16:17] op_sel_hi:[1,0,1]
	v_pk_fma_f32 v[22:23], v[66:67], v[24:25], v[18:19] op_sel_hi:[1,0,1]
	v_pk_mul_f32 v[4:5], v[8:9], v[28:29]
	v_pk_mul_f32 v[6:7], v[10:11], v[30:31]
	v_pk_fma_f32 v[4:5], v[20:21], v[32:33], v[4:5]
	v_pk_fma_f32 v[6:7], v[22:23], v[34:35], v[6:7]
	ds_read_b128 v[52:55], v74 offset:28160
	ds_read_b128 v[56:59], v74 offset:28176
	ds_read_b128 v[36:39], v74 offset:11776
	ds_read_b128 v[40:43], v74 offset:11792
	ds_read_b128 v[44:47], v74 offset:19968
	ds_read_b128 v[48:51], v74 offset:19984
	ds_read_b128 v[60:63], v74 offset:36352
	ds_read_b128 v[64:67], v74 offset:36368
	ds_read_b128 v[28:31], v74 offset:3584
	ds_read_b128 v[32:35], v74 offset:3600
	ds_read_b32 v68, v75 offset:42752
	s_waitcnt lgkmcnt(12)
	v_pk_mul_f32 v[0:1], v[8:9], v[130:131]
	v_pk_mul_f32 v[2:3], v[10:11], v[132:133]
	v_pk_fma_f32 v[0:1], v[20:21], v[134:135], v[0:1]
	v_pk_fma_f32 v[2:3], v[22:23], v[136:137], v[2:3]
	v_pk_add_f32 v[4:5], v[4:5], v[6:7]
	v_pk_mul_f32 v[12:13], v[8:9], v[114:115]
	v_pk_add_f32 v[0:1], v[0:1], v[2:3]
	v_pk_mul_f32 v[14:15], v[10:11], v[116:117]
	v_add_f32_e32 v26, v4, v5
	v_pk_mul_f32 v[16:17], v[20:21], v[118:119]
	v_add_f32_e32 v24, v0, v1
	v_pk_mul_f32 v[18:19], v[22:23], v[120:121]
	v_pk_fma_f32 v[12:13], v[122:123], v[72:73], v[12:13] op_sel_hi:[1,0,1]
	v_add_f32_dpp v26, v26, v26 quad_perm:[1,0,3,2] row_mask:0xf bank_mask:0xf bound_ctrl:1
	v_add_f32_dpp v24, v24, v24 quad_perm:[1,0,3,2] row_mask:0xf bank_mask:0xf bound_ctrl:1
	v_pk_fma_f32 v[14:15], v[124:125], v[72:73], v[14:15] op_sel_hi:[1,0,1]
	v_pk_fma_f32 v[16:17], v[126:127], v[72:73], v[16:17] op_sel_hi:[1,0,1]
	v_add_f32_dpp v26, v26, v26 quad_perm:[2,3,0,1] row_mask:0xf bank_mask:0xf bound_ctrl:1
	v_add_f32_dpp v24, v24, v24 quad_perm:[2,3,0,1] row_mask:0xf bank_mask:0xf bound_ctrl:1
	v_pk_fma_f32 v[18:19], v[128:129], v[72:73], v[18:19] op_sel_hi:[1,0,1]
	v_add_f32_dpp v26, v26, v26 row_half_mirror row_mask:0xf bank_mask:0xf bound_ctrl:1
	v_add_f32_dpp v24, v24, v24 row_half_mirror row_mask:0xf bank_mask:0xf bound_ctrl:1
	ds_write_b32 v76, v26 offset:1536
	v_pk_fma_f32 v[8:9], v[138:139], v[24:25], v[12:13] op_sel_hi:[1,0,1]
	v_pk_fma_f32 v[10:11], v[140:141], v[24:25], v[14:15] op_sel_hi:[1,0,1]
	v_pk_fma_f32 v[20:21], v[142:143], v[24:25], v[16:17] op_sel_hi:[1,0,1]
	v_pk_fma_f32 v[22:23], v[144:145], v[24:25], v[18:19] op_sel_hi:[1,0,1]
	v_pk_mul_f32 v[4:5], v[8:9], v[106:107]
	v_pk_mul_f32 v[6:7], v[10:11], v[108:109]
	v_pk_fma_f32 v[4:5], v[20:21], v[110:111], v[4:5]
	v_pk_fma_f32 v[6:7], v[22:23], v[112:113], v[6:7]
	ds_read_b128 v[130:133], v74 offset:28416
	ds_read_b128 v[134:137], v74 offset:28432
	ds_read_b128 v[114:117], v74 offset:12032
	ds_read_b128 v[118:121], v74 offset:12048
	ds_read_b128 v[122:125], v74 offset:20224
	ds_read_b128 v[126:129], v74 offset:20240
	ds_read_b128 v[138:141], v74 offset:36608
	ds_read_b128 v[142:145], v74 offset:36624
	ds_read_b128 v[106:109], v74 offset:3840
	ds_read_b128 v[110:113], v74 offset:3856
	ds_read_b32 v72, v75 offset:42880
	s_waitcnt lgkmcnt(12)
; __device__ __forceinline__ void rwkv_scan_phase(Frame& F, const bf16* RKV, const float* WAG, const bf16* AGB, const float* k_k, const float* k_a, const float* r_k, bf16* Y, float* BS, float* ST2) {
;     ...
;                 f32x2 r0[4], w0[4], k0[4], a0[4], b0[4], r1[4], w1[4], k1[4], a1[4], b1[4]; float v0, v1;
;                 SC_LOAD(r0, w0, k0, a0, b0, v0, 0);
; #pragma unroll
;                 for (int t = 0; t < SC_T; t += 2) {
;                     SC_LOAD(r1, w1, k1, a1, b1, v1, t + 1);
;                     SC_STEP(r0, w0, k0, a0, b0, v0, t);
;                     if (t + 2 < SC_T) SC_LOAD(r0, w0, k0, a0, b0, v0, t + 2);
;                     SC_STEP(r1, w1, k1, a1, b1, v1, t + 1);
;                 }
	v_pk_mul_f32 v[0:1], v[8:9], v[52:53]
	v_pk_mul_f32 v[2:3], v[10:11], v[54:55]
	v_pk_fma_f32 v[0:1], v[20:21], v[56:57], v[0:1]
	v_pk_fma_f32 v[2:3], v[22:23], v[58:59], v[2:3]
	v_pk_add_f32 v[4:5], v[4:5], v[6:7]
	v_pk_mul_f32 v[12:13], v[8:9], v[36:37]
	v_pk_add_f32 v[0:1], v[0:1], v[2:3]
	v_pk_mul_f32 v[14:15], v[10:11], v[38:39]
	v_add_f32_e32 v26, v4, v5
	v_pk_mul_f32 v[16:17], v[20:21], v[40:41]
	v_add_f32_e32 v24, v0, v1
	v_pk_mul_f32 v[18:19], v[22:23], v[42:43]
	v_pk_fma_f32 v[12:13], v[44:45], v[68:69], v[12:13] op_sel_hi:[1,0,1]
	v_add_f32_dpp v26, v26, v26 quad_perm:[1,0,3,2] row_mask:0xf bank_mask:0xf bound_ctrl:1
	v_add_f32_dpp v24, v24, v24 quad_perm:[1,0,3,2] row_mask:0xf bank_mask:0xf bound_ctrl:1
	v_pk_fma_f32 v[14:15], v[46:47], v[68:69], v[14:15] op_sel_hi:[1,0,1]
	v_pk_fma_f32 v[16:17], v[48:49], v[68:69], v[16:17] op_sel_hi:[1,0,1]
	v_add_f32_dpp v26, v26, v26 quad_perm:[2,3,0,1] row_mask:0xf bank_mask:0xf bound_ctrl:1
	v_add_f32_dpp v24, v24, v24 quad_perm:[2,3,0,1] row_mask:0xf bank_mask:0xf bound_ctrl:1
	v_pk_fma_f32 v[18:19], v[50:51], v[68:69], v[18:19] op_sel_hi:[1,0,1]
	v_add_f32_dpp v26, v26, v26 row_half_mirror row_mask:0xf bank_mask:0xf bound_ctrl:1
	v_add_f32_dpp v24, v24, v24 row_half_mirror row_mask:0xf bank_mask:0xf bound_ctrl:1
	ds_write_b32 v76, v26 offset:1664
	v_pk_fma_f32 v[8:9], v[60:61], v[24:25], v[12:13] op_sel_hi:[1,0,1]
	v_pk_fma_f32 v[10:11], v[62:63], v[24:25], v[14:15] op_sel_hi:[1,0,1]
	v_pk_fma_f32 v[20:21], v[64:65], v[24:25], v[16:17] op_sel_hi:[1,0,1]
	v_pk_fma_f32 v[22:23], v[66:67], v[24:25], v[18:19] op_sel_hi:[1,0,1]
	v_pk_mul_f32 v[4:5], v[8:9], v[28:29]
	v_pk_mul_f32 v[6:7], v[10:11], v[30:31]
	v_pk_fma_f32 v[4:5], v[20:21], v[32:33], v[4:5]
	v_pk_fma_f32 v[6:7], v[22:23], v[34:35], v[6:7]
	ds_read_b128 v[52:55], v74 offset:28672
	ds_read_b128 v[56:59], v74 offset:28688
	ds_read_b128 v[36:39], v74 offset:12288
	ds_read_b128 v[40:43], v74 offset:12304
	ds_read_b128 v[44:47], v74 offset:20480
	ds_read_b128 v[48:51], v74 offset:20496
	ds_read_b128 v[60:63], v74 offset:36864
	ds_read_b128 v[64:67], v74 offset:36880
	ds_read_b128 v[28:31], v74 offset:4096
	ds_read_b128 v[32:35], v74 offset:4112
	ds_read_b32 v68, v75 offset:43008
	s_waitcnt lgkmcnt(12)
	v_pk_mul_f32 v[0:1], v[8:9], v[130:131]
	v_pk_mul_f32 v[2:3], v[10:11], v[132:133]
	v_pk_fma_f32 v[0:1], v[20:21], v[134:135], v[0:1]
	v_pk_fma_f32 v[2:3], v[22:23], v[136:137], v[2:3]
	v_pk_add_f32 v[4:5], v[4:5], v[6:7]
	v_pk_mul_f32 v[12:13], v[8:9], v[114:115]
	v_pk_add_f32 v[0:1], v[0:1], v[2:3]
	v_pk_mul_f32 v[14:15], v[10:11], v[116:117]
	v_add_f32_e32 v26, v4, v5
	v_pk_mul_f32 v[16:17], v[20:21], v[118:119]
	v_add_f32_e32 v24, v0, v1
	v_pk_mul_f32 v[18:19], v[22:23], v[120:121]
	v_pk_fma_f32 v[12:13], v[122:123], v[72:73], v[12:13] op_sel_hi:[1,0,1]
	v_add_f32_dpp v26, v26, v26 quad_perm:[1,0,3,2] row_mask:0xf bank_mask:0xf bound_ctrl:1
	v_add_f32_dpp v24, v24, v24 quad_perm:[1,0,3,2] row_mask:0xf bank_mask:0xf bound_ctrl:1
	v_pk_fma_f32 v[14:15], v[124:125], v[72:73], v[14:15] op_sel_hi:[1,0,1]
	v_pk_fma_f32 v[16:17], v[126:127], v[72:73], v[16:17] op_sel_hi:[1,0,1]
	v_add_f32_dpp v26, v26, v26 quad_perm:[2,3,0,1] row_mask:0xf bank_mask:0xf bound_ctrl:1
	v_add_f32_dpp v24, v24, v24 quad_perm:[2,3,0,1] row_mask:0xf bank_mask:0xf bound_ctrl:1
	v_pk_fma_f32 v[18:19], v[128:129], v[72:73], v[18:19] op_sel_hi:[1,0,1]
	v_add_f32_dpp v26, v26, v26 row_half_mirror row_mask:0xf bank_mask:0xf bound_ctrl:1
	v_add_f32_dpp v24, v24, v24 row_half_mirror row_mask:0xf bank_mask:0xf bound_ctrl:1
	ds_write_b32 v76, v26 offset:1792
	v_pk_fma_f32 v[8:9], v[138:139], v[24:25], v[12:13] op_sel_hi:[1,0,1]
	v_pk_fma_f32 v[10:11], v[140:141], v[24:25], v[14:15] op_sel_hi:[1,0,1]
	v_pk_fma_f32 v[20:21], v[142:143], v[24:25], v[16:17] op_sel_hi:[1,0,1]
	v_pk_fma_f32 v[22:23], v[144:145], v[24:25], v[18:19] op_sel_hi:[1,0,1]
	v_pk_mul_f32 v[4:5], v[8:9], v[106:107]
	v_pk_mul_f32 v[6:7], v[10:11], v[108:109]
	v_pk_fma_f32 v[4:5], v[20:21], v[110:111], v[4:5]
	v_pk_fma_f32 v[6:7], v[22:23], v[112:113], v[6:7]
	ds_read_b128 v[130:133], v74 offset:28928
	ds_read_b128 v[134:137], v74 offset:28944
	ds_read_b128 v[114:117], v74 offset:12544
	ds_read_b128 v[118:121], v74 offset:12560
	ds_read_b128 v[122:125], v74 offset:20736
	ds_read_b128 v[126:129], v74 offset:20752
	ds_read_b128 v[138:141], v74 offset:37120
	ds_read_b128 v[142:145], v74 offset:37136
	ds_read_b128 v[106:109], v74 offset:4352
	ds_read_b128 v[110:113], v74 offset:4368
	ds_read_b32 v72, v75 offset:43136
	s_waitcnt lgkmcnt(12)
; __device__ __forceinline__ void rwkv_scan_phase(Frame& F, const bf16* RKV, const float* WAG, const bf16* AGB, const float* k_k, const float* k_a, const float* r_k, bf16* Y, float* BS, float* ST2) {
;     ...
;                 f32x2 r0[4], w0[4], k0[4], a0[4], b0[4], r1[4], w1[4], k1[4], a1[4], b1[4]; float v0, v1;
;                 SC_LOAD(r0, w0, k0, a0, b0, v0, 0);
; #pragma unroll
;                 for (int t = 0; t < SC_T; t += 2) {
;                     SC_LOAD(r1, w1, k1, a1, b1, v1, t + 1);
;                     SC_STEP(r0, w0, k0, a0, b0, v0, t);
;                     if (t + 2 < SC_T) SC_LOAD(r0, w0, k0, a0, b0, v0, t + 2);
;                     SC_STEP(r1, w1, k1, a1, b1, v1, t + 1);
;                 }
	v_pk_mul_f32 v[0:1], v[8:9], v[52:53]
	v_pk_mul_f32 v[2:3], v[10:11], v[54:55]
	v_pk_fma_f32 v[0:1], v[20:21], v[56:57], v[0:1]
	v_pk_fma_f32 v[2:3], v[22:23], v[58:59], v[2:3]
	v_pk_add_f32 v[4:5], v[4:5], v[6:7]
	v_pk_mul_f32 v[12:13], v[8:9], v[36:37]
	v_pk_add_f32 v[0:1], v[0:1], v[2:3]
	v_pk_mul_f32 v[14:15], v[10:11], v[38:39]
	v_add_f32_e32 v26, v4, v5
	v_pk_mul_f32 v[16:17], v[20:21], v[40:41]
	v_add_f32_e32 v24, v0, v1
	v_pk_mul_f32 v[18:19], v[22:23], v[42:43]
	v_pk_fma_f32 v[12:13], v[44:45], v[68:69], v[12:13] op_sel_hi:[1,0,1]
	v_add_f32_dpp v26, v26, v26 quad_perm:[1,0,3,2] row_mask:0xf bank_mask:0xf bound_ctrl:1
	v_add_f32_dpp v24, v24, v24 quad_perm:[1,0,3,2] row_mask:0xf bank_mask:0xf bound_ctrl:1
	v_pk_fma_f32 v[14:15], v[46:47], v[68:69], v[14:15] op_sel_hi:[1,0,1]
	v_pk_fma_f32 v[16:17], v[48:49], v[68:69], v[16:17] op_sel_hi:[1,0,1]
	v_add_f32_dpp v26, v26, v26 quad_perm:[2,3,0,1] row_mask:0xf bank_mask:0xf bound_ctrl:1
	v_add_f32_dpp v24, v24, v24 quad_perm:[2,3,0,1] row_mask:0xf bank_mask:0xf bound_ctrl:1
	v_pk_fma_f32 v[18:19], v[50:51], v[68:69], v[18:19] op_sel_hi:[1,0,1]
	v_add_f32_dpp v26, v26, v26 row_half_mirror row_mask:0xf bank_mask:0xf bound_ctrl:1
	v_add_f32_dpp v24, v24, v24 row_half_mirror row_mask:0xf bank_mask:0xf bound_ctrl:1
	ds_write_b32 v76, v26 offset:1920
	v_pk_fma_f32 v[8:9], v[60:61], v[24:25], v[12:13] op_sel_hi:[1,0,1]
	v_pk_fma_f32 v[10:11], v[62:63], v[24:25], v[14:15] op_sel_hi:[1,0,1]
	v_pk_fma_f32 v[20:21], v[64:65], v[24:25], v[16:17] op_sel_hi:[1,0,1]
	v_pk_fma_f32 v[22:23], v[66:67], v[24:25], v[18:19] op_sel_hi:[1,0,1]
	v_pk_mul_f32 v[4:5], v[8:9], v[28:29]
	v_pk_mul_f32 v[6:7], v[10:11], v[30:31]
	v_pk_fma_f32 v[4:5], v[20:21], v[32:33], v[4:5]
	v_pk_fma_f32 v[6:7], v[22:23], v[34:35], v[6:7]
	ds_read_b128 v[52:55], v74 offset:29184
	ds_read_b128 v[56:59], v74 offset:29200
	ds_read_b128 v[36:39], v74 offset:12800
	ds_read_b128 v[40:43], v74 offset:12816
	ds_read_b128 v[44:47], v74 offset:20992
	ds_read_b128 v[48:51], v74 offset:21008
	ds_read_b128 v[60:63], v74 offset:37376
	ds_read_b128 v[64:67], v74 offset:37392
	ds_read_b128 v[28:31], v74 offset:4608
	ds_read_b128 v[32:35], v74 offset:4624
	ds_read_b32 v68, v75 offset:43264
	s_waitcnt lgkmcnt(12)
	v_pk_mul_f32 v[0:1], v[8:9], v[130:131]
	v_pk_mul_f32 v[2:3], v[10:11], v[132:133]
	v_pk_fma_f32 v[0:1], v[20:21], v[134:135], v[0:1]
	v_pk_fma_f32 v[2:3], v[22:23], v[136:137], v[2:3]
	v_pk_add_f32 v[4:5], v[4:5], v[6:7]
	v_pk_mul_f32 v[12:13], v[8:9], v[114:115]
	v_pk_add_f32 v[0:1], v[0:1], v[2:3]
	v_pk_mul_f32 v[14:15], v[10:11], v[116:117]
	v_add_f32_e32 v26, v4, v5
	v_pk_mul_f32 v[16:17], v[20:21], v[118:119]
	v_add_f32_e32 v24, v0, v1
	v_pk_mul_f32 v[18:19], v[22:23], v[120:121]
	v_pk_fma_f32 v[12:13], v[122:123], v[72:73], v[12:13] op_sel_hi:[1,0,1]
	v_add_f32_dpp v26, v26, v26 quad_perm:[1,0,3,2] row_mask:0xf bank_mask:0xf bound_ctrl:1
	v_add_f32_dpp v24, v24, v24 quad_perm:[1,0,3,2] row_mask:0xf bank_mask:0xf bound_ctrl:1
	v_pk_fma_f32 v[14:15], v[124:125], v[72:73], v[14:15] op_sel_hi:[1,0,1]
	v_pk_fma_f32 v[16:17], v[126:127], v[72:73], v[16:17] op_sel_hi:[1,0,1]
	v_add_f32_dpp v26, v26, v26 quad_perm:[2,3,0,1] row_mask:0xf bank_mask:0xf bound_ctrl:1
	v_add_f32_dpp v24, v24, v24 quad_perm:[2,3,0,1] row_mask:0xf bank_mask:0xf bound_ctrl:1
	v_pk_fma_f32 v[18:19], v[128:129], v[72:73], v[18:19] op_sel_hi:[1,0,1]
	v_add_f32_dpp v26, v26, v26 row_half_mirror row_mask:0xf bank_mask:0xf bound_ctrl:1
	v_add_f32_dpp v24, v24, v24 row_half_mirror row_mask:0xf bank_mask:0xf bound_ctrl:1
	ds_write_b32 v76, v26 offset:2048
	v_pk_fma_f32 v[8:9], v[138:139], v[24:25], v[12:13] op_sel_hi:[1,0,1]
	v_pk_fma_f32 v[10:11], v[140:141], v[24:25], v[14:15] op_sel_hi:[1,0,1]
	v_pk_fma_f32 v[20:21], v[142:143], v[24:25], v[16:17] op_sel_hi:[1,0,1]
	v_pk_fma_f32 v[22:23], v[144:145], v[24:25], v[18:19] op_sel_hi:[1,0,1]
	v_pk_mul_f32 v[4:5], v[8:9], v[106:107]
	v_pk_mul_f32 v[6:7], v[10:11], v[108:109]
	v_pk_fma_f32 v[4:5], v[20:21], v[110:111], v[4:5]
	v_pk_fma_f32 v[6:7], v[22:23], v[112:113], v[6:7]
	ds_read_b128 v[130:133], v74 offset:29440
	ds_read_b128 v[134:137], v74 offset:29456
	ds_read_b128 v[114:117], v74 offset:13056
	ds_read_b128 v[118:121], v74 offset:13072
	ds_read_b128 v[122:125], v74 offset:21248
	ds_read_b128 v[126:129], v74 offset:21264
	ds_read_b128 v[138:141], v74 offset:37632
	ds_read_b128 v[142:145], v74 offset:37648
	ds_read_b128 v[106:109], v74 offset:4864
	ds_read_b128 v[110:113], v74 offset:4880
	ds_read_b32 v72, v75 offset:43392
	s_waitcnt lgkmcnt(12)
; __device__ __forceinline__ void rwkv_scan_phase(Frame& F, const bf16* RKV, const float* WAG, const bf16* AGB, const float* k_k, const float* k_a, const float* r_k, bf16* Y, float* BS, float* ST2) {
;     ...
;                 f32x2 r0[4], w0[4], k0[4], a0[4], b0[4], r1[4], w1[4], k1[4], a1[4], b1[4]; float v0, v1;
;                 SC_LOAD(r0, w0, k0, a0, b0, v0, 0);
; #pragma unroll
;                 for (int t = 0; t < SC_T; t += 2) {
;                     SC_LOAD(r1, w1, k1, a1, b1, v1, t + 1);
;                     SC_STEP(r0, w0, k0, a0, b0, v0, t);
;                     if (t + 2 < SC_T) SC_LOAD(r0, w0, k0, a0, b0, v0, t + 2);
;                     SC_STEP(r1, w1, k1, a1, b1, v1, t + 1);
;                 }
	v_pk_mul_f32 v[0:1], v[8:9], v[52:53]
	v_pk_mul_f32 v[2:3], v[10:11], v[54:55]
	v_pk_fma_f32 v[0:1], v[20:21], v[56:57], v[0:1]
	v_pk_fma_f32 v[2:3], v[22:23], v[58:59], v[2:3]
	v_pk_add_f32 v[4:5], v[4:5], v[6:7]
	v_pk_mul_f32 v[12:13], v[8:9], v[36:37]
	v_pk_add_f32 v[0:1], v[0:1], v[2:3]
	v_pk_mul_f32 v[14:15], v[10:11], v[38:39]
	v_add_f32_e32 v26, v4, v5
	v_pk_mul_f32 v[16:17], v[20:21], v[40:41]
	v_add_f32_e32 v24, v0, v1
	v_pk_mul_f32 v[18:19], v[22:23], v[42:43]
	v_pk_fma_f32 v[12:13], v[44:45], v[68:69], v[12:13] op_sel_hi:[1,0,1]
	v_add_f32_dpp v26, v26, v26 quad_perm:[1,0,3,2] row_mask:0xf bank_mask:0xf bound_ctrl:1
	v_add_f32_dpp v24, v24, v24 quad_perm:[1,0,3,2] row_mask:0xf bank_mask:0xf bound_ctrl:1
	v_pk_fma_f32 v[14:15], v[46:47], v[68:69], v[14:15] op_sel_hi:[1,0,1]
	v_pk_fma_f32 v[16:17], v[48:49], v[68:69], v[16:17] op_sel_hi:[1,0,1]
	v_add_f32_dpp v26, v26, v26 quad_perm:[2,3,0,1] row_mask:0xf bank_mask:0xf bound_ctrl:1
	v_add_f32_dpp v24, v24, v24 quad_perm:[2,3,0,1] row_mask:0xf bank_mask:0xf bound_ctrl:1
	v_pk_fma_f32 v[18:19], v[50:51], v[68:69], v[18:19] op_sel_hi:[1,0,1]
	v_add_f32_dpp v26, v26, v26 row_half_mirror row_mask:0xf bank_mask:0xf bound_ctrl:1
	v_add_f32_dpp v24, v24, v24 row_half_mirror row_mask:0xf bank_mask:0xf bound_ctrl:1
	ds_write_b32 v76, v26 offset:2176
	v_pk_fma_f32 v[8:9], v[60:61], v[24:25], v[12:13] op_sel_hi:[1,0,1]
	v_pk_fma_f32 v[10:11], v[62:63], v[24:25], v[14:15] op_sel_hi:[1,0,1]
	v_pk_fma_f32 v[20:21], v[64:65], v[24:25], v[16:17] op_sel_hi:[1,0,1]
	v_pk_fma_f32 v[22:23], v[66:67], v[24:25], v[18:19] op_sel_hi:[1,0,1]
	v_pk_mul_f32 v[4:5], v[8:9], v[28:29]
	v_pk_mul_f32 v[6:7], v[10:11], v[30:31]
	v_pk_fma_f32 v[4:5], v[20:21], v[32:33], v[4:5]
	v_pk_fma_f32 v[6:7], v[22:23], v[34:35], v[6:7]
	ds_read_b128 v[52:55], v74 offset:29696
	ds_read_b128 v[56:59], v74 offset:29712
	ds_read_b128 v[36:39], v74 offset:13312
	ds_read_b128 v[40:43], v74 offset:13328
	ds_read_b128 v[44:47], v74 offset:21504
	ds_read_b128 v[48:51], v74 offset:21520
	ds_read_b128 v[60:63], v74 offset:37888
	ds_read_b128 v[64:67], v74 offset:37904
	ds_read_b128 v[28:31], v74 offset:5120
	ds_read_b128 v[32:35], v74 offset:5136
	ds_read_b32 v68, v75 offset:43520
	s_waitcnt lgkmcnt(12)
	v_pk_mul_f32 v[0:1], v[8:9], v[130:131]
	v_pk_mul_f32 v[2:3], v[10:11], v[132:133]
	v_pk_fma_f32 v[0:1], v[20:21], v[134:135], v[0:1]
	v_pk_fma_f32 v[2:3], v[22:23], v[136:137], v[2:3]
	v_pk_add_f32 v[4:5], v[4:5], v[6:7]
	v_pk_mul_f32 v[12:13], v[8:9], v[114:115]
	v_pk_add_f32 v[0:1], v[0:1], v[2:3]
	v_pk_mul_f32 v[14:15], v[10:11], v[116:117]
	v_add_f32_e32 v26, v4, v5
	v_pk_mul_f32 v[16:17], v[20:21], v[118:119]
	v_add_f32_e32 v24, v0, v1
	v_pk_mul_f32 v[18:19], v[22:23], v[120:121]
	v_pk_fma_f32 v[12:13], v[122:123], v[72:73], v[12:13] op_sel_hi:[1,0,1]
	v_add_f32_dpp v26, v26, v26 quad_perm:[1,0,3,2] row_mask:0xf bank_mask:0xf bound_ctrl:1
	v_add_f32_dpp v24, v24, v24 quad_perm:[1,0,3,2] row_mask:0xf bank_mask:0xf bound_ctrl:1
	v_pk_fma_f32 v[14:15], v[124:125], v[72:73], v[14:15] op_sel_hi:[1,0,1]
	v_pk_fma_f32 v[16:17], v[126:127], v[72:73], v[16:17] op_sel_hi:[1,0,1]
	v_add_f32_dpp v26, v26, v26 quad_perm:[2,3,0,1] row_mask:0xf bank_mask:0xf bound_ctrl:1
	v_add_f32_dpp v24, v24, v24 quad_perm:[2,3,0,1] row_mask:0xf bank_mask:0xf bound_ctrl:1
	v_pk_fma_f32 v[18:19], v[128:129], v[72:73], v[18:19] op_sel_hi:[1,0,1]
	v_add_f32_dpp v26, v26, v26 row_half_mirror row_mask:0xf bank_mask:0xf bound_ctrl:1
	v_add_f32_dpp v24, v24, v24 row_half_mirror row_mask:0xf bank_mask:0xf bound_ctrl:1
	ds_write_b32 v76, v26 offset:2304
	v_pk_fma_f32 v[8:9], v[138:139], v[24:25], v[12:13] op_sel_hi:[1,0,1]
	v_pk_fma_f32 v[10:11], v[140:141], v[24:25], v[14:15] op_sel_hi:[1,0,1]
	v_pk_fma_f32 v[20:21], v[142:143], v[24:25], v[16:17] op_sel_hi:[1,0,1]
	v_pk_fma_f32 v[22:23], v[144:145], v[24:25], v[18:19] op_sel_hi:[1,0,1]
	v_pk_mul_f32 v[4:5], v[8:9], v[106:107]
	v_pk_mul_f32 v[6:7], v[10:11], v[108:109]
	v_pk_fma_f32 v[4:5], v[20:21], v[110:111], v[4:5]
	v_pk_fma_f32 v[6:7], v[22:23], v[112:113], v[6:7]
	ds_read_b128 v[130:133], v74 offset:29952
	ds_read_b128 v[134:137], v74 offset:29968
	ds_read_b128 v[114:117], v74 offset:13568
	ds_read_b128 v[118:121], v74 offset:13584
	ds_read_b128 v[122:125], v74 offset:21760
	ds_read_b128 v[126:129], v74 offset:21776
	ds_read_b128 v[138:141], v74 offset:38144
	ds_read_b128 v[142:145], v74 offset:38160
	ds_read_b128 v[106:109], v74 offset:5376
	ds_read_b128 v[110:113], v74 offset:5392
	ds_read_b32 v72, v75 offset:43648
	s_waitcnt lgkmcnt(12)
; __device__ __forceinline__ void rwkv_scan_phase(Frame& F, const bf16* RKV, const float* WAG, const bf16* AGB, const float* k_k, const float* k_a, const float* r_k, bf16* Y, float* BS, float* ST2) {
;     ...
;                 f32x2 r0[4], w0[4], k0[4], a0[4], b0[4], r1[4], w1[4], k1[4], a1[4], b1[4]; float v0, v1;
;                 SC_LOAD(r0, w0, k0, a0, b0, v0, 0);
; #pragma unroll
;                 for (int t = 0; t < SC_T; t += 2) {
;                     SC_LOAD(r1, w1, k1, a1, b1, v1, t + 1);
;                     SC_STEP(r0, w0, k0, a0, b0, v0, t);
;                     if (t + 2 < SC_T) SC_LOAD(r0, w0, k0, a0, b0, v0, t + 2);
;                     SC_STEP(r1, w1, k1, a1, b1, v1, t + 1);
;                 }
	v_pk_mul_f32 v[0:1], v[8:9], v[52:53]
	v_pk_mul_f32 v[2:3], v[10:11], v[54:55]
	v_pk_fma_f32 v[0:1], v[20:21], v[56:57], v[0:1]
	v_pk_fma_f32 v[2:3], v[22:23], v[58:59], v[2:3]
	v_pk_add_f32 v[4:5], v[4:5], v[6:7]
	v_pk_mul_f32 v[12:13], v[8:9], v[36:37]
	v_pk_add_f32 v[0:1], v[0:1], v[2:3]
	v_pk_mul_f32 v[14:15], v[10:11], v[38:39]
	v_add_f32_e32 v26, v4, v5
	v_pk_mul_f32 v[16:17], v[20:21], v[40:41]
	v_add_f32_e32 v24, v0, v1
	v_pk_mul_f32 v[18:19], v[22:23], v[42:43]
	v_pk_fma_f32 v[12:13], v[44:45], v[68:69], v[12:13] op_sel_hi:[1,0,1]
	v_add_f32_dpp v26, v26, v26 quad_perm:[1,0,3,2] row_mask:0xf bank_mask:0xf bound_ctrl:1
	v_add_f32_dpp v24, v24, v24 quad_perm:[1,0,3,2] row_mask:0xf bank_mask:0xf bound_ctrl:1
	v_pk_fma_f32 v[14:15], v[46:47], v[68:69], v[14:15] op_sel_hi:[1,0,1]
	v_pk_fma_f32 v[16:17], v[48:49], v[68:69], v[16:17] op_sel_hi:[1,0,1]
	v_add_f32_dpp v26, v26, v26 quad_perm:[2,3,0,1] row_mask:0xf bank_mask:0xf bound_ctrl:1
	v_add_f32_dpp v24, v24, v24 quad_perm:[2,3,0,1] row_mask:0xf bank_mask:0xf bound_ctrl:1
	v_pk_fma_f32 v[18:19], v[50:51], v[68:69], v[18:19] op_sel_hi:[1,0,1]
	v_add_f32_dpp v26, v26, v26 row_half_mirror row_mask:0xf bank_mask:0xf bound_ctrl:1
	v_add_f32_dpp v24, v24, v24 row_half_mirror row_mask:0xf bank_mask:0xf bound_ctrl:1
	ds_write_b32 v76, v26 offset:2432
	v_pk_fma_f32 v[8:9], v[60:61], v[24:25], v[12:13] op_sel_hi:[1,0,1]
	v_pk_fma_f32 v[10:11], v[62:63], v[24:25], v[14:15] op_sel_hi:[1,0,1]
	v_pk_fma_f32 v[20:21], v[64:65], v[24:25], v[16:17] op_sel_hi:[1,0,1]
	v_pk_fma_f32 v[22:23], v[66:67], v[24:25], v[18:19] op_sel_hi:[1,0,1]
	v_pk_mul_f32 v[4:5], v[8:9], v[28:29]
	v_pk_mul_f32 v[6:7], v[10:11], v[30:31]
	v_pk_fma_f32 v[4:5], v[20:21], v[32:33], v[4:5]
	v_pk_fma_f32 v[6:7], v[22:23], v[34:35], v[6:7]
	ds_read_b128 v[52:55], v74 offset:30208
	ds_read_b128 v[56:59], v74 offset:30224
	ds_read_b128 v[36:39], v74 offset:13824
	ds_read_b128 v[40:43], v74 offset:13840
	ds_read_b128 v[44:47], v74 offset:22016
	ds_read_b128 v[48:51], v74 offset:22032
	ds_read_b128 v[60:63], v74 offset:38400
	ds_read_b128 v[64:67], v74 offset:38416
	ds_read_b128 v[28:31], v74 offset:5632
	ds_read_b128 v[32:35], v74 offset:5648
	ds_read_b32 v68, v75 offset:43776
	s_waitcnt lgkmcnt(12)
	v_pk_mul_f32 v[0:1], v[8:9], v[130:131]
	v_pk_mul_f32 v[2:3], v[10:11], v[132:133]
	v_pk_fma_f32 v[0:1], v[20:21], v[134:135], v[0:1]
	v_pk_fma_f32 v[2:3], v[22:23], v[136:137], v[2:3]
	v_pk_add_f32 v[4:5], v[4:5], v[6:7]
	v_pk_mul_f32 v[12:13], v[8:9], v[114:115]
	v_pk_add_f32 v[0:1], v[0:1], v[2:3]
	v_pk_mul_f32 v[14:15], v[10:11], v[116:117]
	v_add_f32_e32 v26, v4, v5
	v_pk_mul_f32 v[16:17], v[20:21], v[118:119]
	v_add_f32_e32 v24, v0, v1
	v_pk_mul_f32 v[18:19], v[22:23], v[120:121]
	v_pk_fma_f32 v[12:13], v[122:123], v[72:73], v[12:13] op_sel_hi:[1,0,1]
	v_add_f32_dpp v26, v26, v26 quad_perm:[1,0,3,2] row_mask:0xf bank_mask:0xf bound_ctrl:1
	v_add_f32_dpp v24, v24, v24 quad_perm:[1,0,3,2] row_mask:0xf bank_mask:0xf bound_ctrl:1
	v_pk_fma_f32 v[14:15], v[124:125], v[72:73], v[14:15] op_sel_hi:[1,0,1]
	v_pk_fma_f32 v[16:17], v[126:127], v[72:73], v[16:17] op_sel_hi:[1,0,1]
	v_add_f32_dpp v26, v26, v26 quad_perm:[2,3,0,1] row_mask:0xf bank_mask:0xf bound_ctrl:1
	v_add_f32_dpp v24, v24, v24 quad_perm:[2,3,0,1] row_mask:0xf bank_mask:0xf bound_ctrl:1
	v_pk_fma_f32 v[18:19], v[128:129], v[72:73], v[18:19] op_sel_hi:[1,0,1]
	v_add_f32_dpp v26, v26, v26 row_half_mirror row_mask:0xf bank_mask:0xf bound_ctrl:1
	v_add_f32_dpp v24, v24, v24 row_half_mirror row_mask:0xf bank_mask:0xf bound_ctrl:1
	ds_write_b32 v76, v26 offset:2560
	v_pk_fma_f32 v[8:9], v[138:139], v[24:25], v[12:13] op_sel_hi:[1,0,1]
	v_pk_fma_f32 v[10:11], v[140:141], v[24:25], v[14:15] op_sel_hi:[1,0,1]
	v_pk_fma_f32 v[20:21], v[142:143], v[24:25], v[16:17] op_sel_hi:[1,0,1]
	v_pk_fma_f32 v[22:23], v[144:145], v[24:25], v[18:19] op_sel_hi:[1,0,1]
	v_pk_mul_f32 v[4:5], v[8:9], v[106:107]
	v_pk_mul_f32 v[6:7], v[10:11], v[108:109]
	v_pk_fma_f32 v[4:5], v[20:21], v[110:111], v[4:5]
	v_pk_fma_f32 v[6:7], v[22:23], v[112:113], v[6:7]
	ds_read_b128 v[130:133], v74 offset:30464
	ds_read_b128 v[134:137], v74 offset:30480
	ds_read_b128 v[114:117], v74 offset:14080
	ds_read_b128 v[118:121], v74 offset:14096
	ds_read_b128 v[122:125], v74 offset:22272
	ds_read_b128 v[126:129], v74 offset:22288
	ds_read_b128 v[138:141], v74 offset:38656
	ds_read_b128 v[142:145], v74 offset:38672
	ds_read_b128 v[106:109], v74 offset:5888
	ds_read_b128 v[110:113], v74 offset:5904
	ds_read_b32 v72, v75 offset:43904
	s_waitcnt lgkmcnt(12)
; __device__ __forceinline__ void rwkv_scan_phase(Frame& F, const bf16* RKV, const float* WAG, const bf16* AGB, const float* k_k, const float* k_a, const float* r_k, bf16* Y, float* BS, float* ST2) {
;     ...
;                 f32x2 r0[4], w0[4], k0[4], a0[4], b0[4], r1[4], w1[4], k1[4], a1[4], b1[4]; float v0, v1;
;                 SC_LOAD(r0, w0, k0, a0, b0, v0, 0);
; #pragma unroll
;                 for (int t = 0; t < SC_T; t += 2) {
;                     SC_LOAD(r1, w1, k1, a1, b1, v1, t + 1);
;                     SC_STEP(r0, w0, k0, a0, b0, v0, t);
;                     if (t + 2 < SC_T) SC_LOAD(r0, w0, k0, a0, b0, v0, t + 2);
;                     SC_STEP(r1, w1, k1, a1, b1, v1, t + 1);
;                 }
	v_pk_mul_f32 v[0:1], v[8:9], v[52:53]
	v_pk_mul_f32 v[2:3], v[10:11], v[54:55]
	v_pk_fma_f32 v[0:1], v[20:21], v[56:57], v[0:1]
	v_pk_fma_f32 v[2:3], v[22:23], v[58:59], v[2:3]
	v_pk_add_f32 v[4:5], v[4:5], v[6:7]
	v_pk_mul_f32 v[12:13], v[8:9], v[36:37]
	v_pk_add_f32 v[0:1], v[0:1], v[2:3]
	v_pk_mul_f32 v[14:15], v[10:11], v[38:39]
	v_add_f32_e32 v26, v4, v5
	v_pk_mul_f32 v[16:17], v[20:21], v[40:41]
	v_add_f32_e32 v24, v0, v1
	v_pk_mul_f32 v[18:19], v[22:23], v[42:43]
	v_pk_fma_f32 v[12:13], v[44:45], v[68:69], v[12:13] op_sel_hi:[1,0,1]
	v_add_f32_dpp v26, v26, v26 quad_perm:[1,0,3,2] row_mask:0xf bank_mask:0xf bound_ctrl:1
	v_add_f32_dpp v24, v24, v24 quad_perm:[1,0,3,2] row_mask:0xf bank_mask:0xf bound_ctrl:1
	v_pk_fma_f32 v[14:15], v[46:47], v[68:69], v[14:15] op_sel_hi:[1,0,1]
	v_pk_fma_f32 v[16:17], v[48:49], v[68:69], v[16:17] op_sel_hi:[1,0,1]
	v_add_f32_dpp v26, v26, v26 quad_perm:[2,3,0,1] row_mask:0xf bank_mask:0xf bound_ctrl:1
	v_add_f32_dpp v24, v24, v24 quad_perm:[2,3,0,1] row_mask:0xf bank_mask:0xf bound_ctrl:1
	v_pk_fma_f32 v[18:19], v[50:51], v[68:69], v[18:19] op_sel_hi:[1,0,1]
	v_add_f32_dpp v26, v26, v26 row_half_mirror row_mask:0xf bank_mask:0xf bound_ctrl:1
	v_add_f32_dpp v24, v24, v24 row_half_mirror row_mask:0xf bank_mask:0xf bound_ctrl:1
	ds_write_b32 v76, v26 offset:2688
	v_pk_fma_f32 v[8:9], v[60:61], v[24:25], v[12:13] op_sel_hi:[1,0,1]
	v_pk_fma_f32 v[10:11], v[62:63], v[24:25], v[14:15] op_sel_hi:[1,0,1]
	v_pk_fma_f32 v[20:21], v[64:65], v[24:25], v[16:17] op_sel_hi:[1,0,1]
	v_pk_fma_f32 v[22:23], v[66:67], v[24:25], v[18:19] op_sel_hi:[1,0,1]
	v_pk_mul_f32 v[4:5], v[8:9], v[28:29]
	v_pk_mul_f32 v[6:7], v[10:11], v[30:31]
	v_pk_fma_f32 v[4:5], v[20:21], v[32:33], v[4:5]
	v_pk_fma_f32 v[6:7], v[22:23], v[34:35], v[6:7]
	ds_read_b128 v[52:55], v74 offset:30720
	ds_read_b128 v[56:59], v74 offset:30736
	ds_read_b128 v[36:39], v74 offset:14336
	ds_read_b128 v[40:43], v74 offset:14352
	ds_read_b128 v[44:47], v74 offset:22528
	ds_read_b128 v[48:51], v74 offset:22544
	ds_read_b128 v[60:63], v74 offset:38912
	ds_read_b128 v[64:67], v74 offset:38928
	ds_read_b128 v[28:31], v74 offset:6144
	ds_read_b128 v[32:35], v74 offset:6160
	ds_read_b32 v68, v75 offset:44032
	s_waitcnt lgkmcnt(12)
	v_pk_mul_f32 v[0:1], v[8:9], v[130:131]
	v_pk_mul_f32 v[2:3], v[10:11], v[132:133]
	v_pk_fma_f32 v[0:1], v[20:21], v[134:135], v[0:1]
	v_pk_fma_f32 v[2:3], v[22:23], v[136:137], v[2:3]
	v_pk_add_f32 v[4:5], v[4:5], v[6:7]
	v_pk_mul_f32 v[12:13], v[8:9], v[114:115]
	v_pk_add_f32 v[0:1], v[0:1], v[2:3]
	v_pk_mul_f32 v[14:15], v[10:11], v[116:117]
	v_add_f32_e32 v26, v4, v5
	v_pk_mul_f32 v[16:17], v[20:21], v[118:119]
	v_add_f32_e32 v24, v0, v1
	v_pk_mul_f32 v[18:19], v[22:23], v[120:121]
	v_pk_fma_f32 v[12:13], v[122:123], v[72:73], v[12:13] op_sel_hi:[1,0,1]
	v_add_f32_dpp v26, v26, v26 quad_perm:[1,0,3,2] row_mask:0xf bank_mask:0xf bound_ctrl:1
	v_add_f32_dpp v24, v24, v24 quad_perm:[1,0,3,2] row_mask:0xf bank_mask:0xf bound_ctrl:1
	v_pk_fma_f32 v[14:15], v[124:125], v[72:73], v[14:15] op_sel_hi:[1,0,1]
	v_pk_fma_f32 v[16:17], v[126:127], v[72:73], v[16:17] op_sel_hi:[1,0,1]
	v_add_f32_dpp v26, v26, v26 quad_perm:[2,3,0,1] row_mask:0xf bank_mask:0xf bound_ctrl:1
	v_add_f32_dpp v24, v24, v24 quad_perm:[2,3,0,1] row_mask:0xf bank_mask:0xf bound_ctrl:1
	v_pk_fma_f32 v[18:19], v[128:129], v[72:73], v[18:19] op_sel_hi:[1,0,1]
	v_add_f32_dpp v26, v26, v26 row_half_mirror row_mask:0xf bank_mask:0xf bound_ctrl:1
	v_add_f32_dpp v24, v24, v24 row_half_mirror row_mask:0xf bank_mask:0xf bound_ctrl:1
	ds_write_b32 v76, v26 offset:2816
	v_pk_fma_f32 v[8:9], v[138:139], v[24:25], v[12:13] op_sel_hi:[1,0,1]
	v_pk_fma_f32 v[10:11], v[140:141], v[24:25], v[14:15] op_sel_hi:[1,0,1]
	v_pk_fma_f32 v[20:21], v[142:143], v[24:25], v[16:17] op_sel_hi:[1,0,1]
	v_pk_fma_f32 v[22:23], v[144:145], v[24:25], v[18:19] op_sel_hi:[1,0,1]
	v_pk_mul_f32 v[4:5], v[8:9], v[106:107]
	v_pk_mul_f32 v[6:7], v[10:11], v[108:109]
	v_pk_fma_f32 v[4:5], v[20:21], v[110:111], v[4:5]
	v_pk_fma_f32 v[6:7], v[22:23], v[112:113], v[6:7]
	ds_read_b128 v[130:133], v74 offset:30976
	ds_read_b128 v[134:137], v74 offset:30992
	ds_read_b128 v[114:117], v74 offset:14592
	ds_read_b128 v[118:121], v74 offset:14608
	ds_read_b128 v[122:125], v74 offset:22784
	ds_read_b128 v[126:129], v74 offset:22800
	ds_read_b128 v[138:141], v74 offset:39168
	ds_read_b128 v[142:145], v74 offset:39184
	ds_read_b128 v[106:109], v74 offset:6400
	ds_read_b128 v[110:113], v74 offset:6416
	ds_read_b32 v72, v75 offset:44160
	s_waitcnt lgkmcnt(12)
; __device__ __forceinline__ void rwkv_scan_phase(Frame& F, const bf16* RKV, const float* WAG, const bf16* AGB, const float* k_k, const float* k_a, const float* r_k, bf16* Y, float* BS, float* ST2) {
;     ...
;                 f32x2 r0[4], w0[4], k0[4], a0[4], b0[4], r1[4], w1[4], k1[4], a1[4], b1[4]; float v0, v1;
;                 SC_LOAD(r0, w0, k0, a0, b0, v0, 0);
; #pragma unroll
;                 for (int t = 0; t < SC_T; t += 2) {
;                     SC_LOAD(r1, w1, k1, a1, b1, v1, t + 1);
;                     SC_STEP(r0, w0, k0, a0, b0, v0, t);
;                     if (t + 2 < SC_T) SC_LOAD(r0, w0, k0, a0, b0, v0, t + 2);
;                     SC_STEP(r1, w1, k1, a1, b1, v1, t + 1);
;                 }
	v_pk_mul_f32 v[0:1], v[8:9], v[52:53]
	v_pk_mul_f32 v[2:3], v[10:11], v[54:55]
	v_pk_fma_f32 v[0:1], v[20:21], v[56:57], v[0:1]
	v_pk_fma_f32 v[2:3], v[22:23], v[58:59], v[2:3]
	v_pk_add_f32 v[4:5], v[4:5], v[6:7]
	v_pk_mul_f32 v[12:13], v[8:9], v[36:37]
	v_pk_add_f32 v[0:1], v[0:1], v[2:3]
	v_pk_mul_f32 v[14:15], v[10:11], v[38:39]
	v_add_f32_e32 v26, v4, v5
	v_pk_mul_f32 v[16:17], v[20:21], v[40:41]
	v_add_f32_e32 v24, v0, v1
	v_pk_mul_f32 v[18:19], v[22:23], v[42:43]
	v_pk_fma_f32 v[12:13], v[44:45], v[68:69], v[12:13] op_sel_hi:[1,0,1]
	v_add_f32_dpp v26, v26, v26 quad_perm:[1,0,3,2] row_mask:0xf bank_mask:0xf bound_ctrl:1
	v_add_f32_dpp v24, v24, v24 quad_perm:[1,0,3,2] row_mask:0xf bank_mask:0xf bound_ctrl:1
	v_pk_fma_f32 v[14:15], v[46:47], v[68:69], v[14:15] op_sel_hi:[1,0,1]
	v_pk_fma_f32 v[16:17], v[48:49], v[68:69], v[16:17] op_sel_hi:[1,0,1]
	v_add_f32_dpp v26, v26, v26 quad_perm:[2,3,0,1] row_mask:0xf bank_mask:0xf bound_ctrl:1
	v_add_f32_dpp v24, v24, v24 quad_perm:[2,3,0,1] row_mask:0xf bank_mask:0xf bound_ctrl:1
	v_pk_fma_f32 v[18:19], v[50:51], v[68:69], v[18:19] op_sel_hi:[1,0,1]
	v_add_f32_dpp v26, v26, v26 row_half_mirror row_mask:0xf bank_mask:0xf bound_ctrl:1
	v_add_f32_dpp v24, v24, v24 row_half_mirror row_mask:0xf bank_mask:0xf bound_ctrl:1
	ds_write_b32 v76, v26 offset:2944
	v_pk_fma_f32 v[8:9], v[60:61], v[24:25], v[12:13] op_sel_hi:[1,0,1]
	v_pk_fma_f32 v[10:11], v[62:63], v[24:25], v[14:15] op_sel_hi:[1,0,1]
	v_pk_fma_f32 v[20:21], v[64:65], v[24:25], v[16:17] op_sel_hi:[1,0,1]
	v_pk_fma_f32 v[22:23], v[66:67], v[24:25], v[18:19] op_sel_hi:[1,0,1]
	v_pk_mul_f32 v[4:5], v[8:9], v[28:29]
	v_pk_mul_f32 v[6:7], v[10:11], v[30:31]
	v_pk_fma_f32 v[4:5], v[20:21], v[32:33], v[4:5]
	v_pk_fma_f32 v[6:7], v[22:23], v[34:35], v[6:7]
	ds_read_b128 v[52:55], v74 offset:31232
	ds_read_b128 v[56:59], v74 offset:31248
	ds_read_b128 v[36:39], v74 offset:14848
	ds_read_b128 v[40:43], v74 offset:14864
	ds_read_b128 v[44:47], v74 offset:23040
	ds_read_b128 v[48:51], v74 offset:23056
	ds_read_b128 v[60:63], v74 offset:39424
	ds_read_b128 v[64:67], v74 offset:39440
	ds_read_b128 v[28:31], v74 offset:6656
	ds_read_b128 v[32:35], v74 offset:6672
	ds_read_b32 v68, v75 offset:44288
	s_waitcnt lgkmcnt(12)
	v_pk_mul_f32 v[0:1], v[8:9], v[130:131]
	v_pk_mul_f32 v[2:3], v[10:11], v[132:133]
	v_pk_fma_f32 v[0:1], v[20:21], v[134:135], v[0:1]
	v_pk_fma_f32 v[2:3], v[22:23], v[136:137], v[2:3]
	v_pk_add_f32 v[4:5], v[4:5], v[6:7]
	v_pk_mul_f32 v[12:13], v[8:9], v[114:115]
	v_pk_add_f32 v[0:1], v[0:1], v[2:3]
	v_pk_mul_f32 v[14:15], v[10:11], v[116:117]
	v_add_f32_e32 v26, v4, v5
	v_pk_mul_f32 v[16:17], v[20:21], v[118:119]
	v_add_f32_e32 v24, v0, v1
	v_pk_mul_f32 v[18:19], v[22:23], v[120:121]
	v_pk_fma_f32 v[12:13], v[122:123], v[72:73], v[12:13] op_sel_hi:[1,0,1]
	v_add_f32_dpp v26, v26, v26 quad_perm:[1,0,3,2] row_mask:0xf bank_mask:0xf bound_ctrl:1
	v_add_f32_dpp v24, v24, v24 quad_perm:[1,0,3,2] row_mask:0xf bank_mask:0xf bound_ctrl:1
	v_pk_fma_f32 v[14:15], v[124:125], v[72:73], v[14:15] op_sel_hi:[1,0,1]
	v_pk_fma_f32 v[16:17], v[126:127], v[72:73], v[16:17] op_sel_hi:[1,0,1]
	v_add_f32_dpp v26, v26, v26 quad_perm:[2,3,0,1] row_mask:0xf bank_mask:0xf bound_ctrl:1
	v_add_f32_dpp v24, v24, v24 quad_perm:[2,3,0,1] row_mask:0xf bank_mask:0xf bound_ctrl:1
	v_pk_fma_f32 v[18:19], v[128:129], v[72:73], v[18:19] op_sel_hi:[1,0,1]
	v_add_f32_dpp v26, v26, v26 row_half_mirror row_mask:0xf bank_mask:0xf bound_ctrl:1
	v_add_f32_dpp v24, v24, v24 row_half_mirror row_mask:0xf bank_mask:0xf bound_ctrl:1
	ds_write_b32 v76, v26 offset:3072
	v_pk_fma_f32 v[8:9], v[138:139], v[24:25], v[12:13] op_sel_hi:[1,0,1]
	v_pk_fma_f32 v[10:11], v[140:141], v[24:25], v[14:15] op_sel_hi:[1,0,1]
	v_pk_fma_f32 v[20:21], v[142:143], v[24:25], v[16:17] op_sel_hi:[1,0,1]
	v_pk_fma_f32 v[22:23], v[144:145], v[24:25], v[18:19] op_sel_hi:[1,0,1]
	v_pk_mul_f32 v[4:5], v[8:9], v[106:107]
	v_pk_mul_f32 v[6:7], v[10:11], v[108:109]
	v_pk_fma_f32 v[4:5], v[20:21], v[110:111], v[4:5]
	v_pk_fma_f32 v[6:7], v[22:23], v[112:113], v[6:7]
	ds_read_b128 v[130:133], v74 offset:31488
	ds_read_b128 v[134:137], v74 offset:31504
	ds_read_b128 v[114:117], v74 offset:15104
	ds_read_b128 v[118:121], v74 offset:15120
	ds_read_b128 v[122:125], v74 offset:23296
	ds_read_b128 v[126:129], v74 offset:23312
	ds_read_b128 v[138:141], v74 offset:39680
	ds_read_b128 v[142:145], v74 offset:39696
	ds_read_b128 v[106:109], v74 offset:6912
	ds_read_b128 v[110:113], v74 offset:6928
	ds_read_b32 v72, v75 offset:44416
	s_waitcnt lgkmcnt(12)
; __device__ __forceinline__ void rwkv_scan_phase(Frame& F, const bf16* RKV, const float* WAG, const bf16* AGB, const float* k_k, const float* k_a, const float* r_k, bf16* Y, float* BS, float* ST2) {
;     ...
;                 f32x2 r0[4], w0[4], k0[4], a0[4], b0[4], r1[4], w1[4], k1[4], a1[4], b1[4]; float v0, v1;
;                 SC_LOAD(r0, w0, k0, a0, b0, v0, 0);
; #pragma unroll
;                 for (int t = 0; t < SC_T; t += 2) {
;                     SC_LOAD(r1, w1, k1, a1, b1, v1, t + 1);
;                     SC_STEP(r0, w0, k0, a0, b0, v0, t);
;                     if (t + 2 < SC_T) SC_LOAD(r0, w0, k0, a0, b0, v0, t + 2);
;                     SC_STEP(r1, w1, k1, a1, b1, v1, t + 1);
;                 }
	v_pk_mul_f32 v[0:1], v[8:9], v[52:53]
	v_pk_mul_f32 v[2:3], v[10:11], v[54:55]
	v_pk_fma_f32 v[0:1], v[20:21], v[56:57], v[0:1]
	v_pk_fma_f32 v[2:3], v[22:23], v[58:59], v[2:3]
	v_pk_add_f32 v[4:5], v[4:5], v[6:7]
	v_pk_mul_f32 v[12:13], v[8:9], v[36:37]
	v_pk_add_f32 v[0:1], v[0:1], v[2:3]
	v_pk_mul_f32 v[14:15], v[10:11], v[38:39]
	v_add_f32_e32 v26, v4, v5
	v_pk_mul_f32 v[16:17], v[20:21], v[40:41]
	v_add_f32_e32 v24, v0, v1
	v_pk_mul_f32 v[18:19], v[22:23], v[42:43]
	v_pk_fma_f32 v[12:13], v[44:45], v[68:69], v[12:13] op_sel_hi:[1,0,1]
	v_add_f32_dpp v26, v26, v26 quad_perm:[1,0,3,2] row_mask:0xf bank_mask:0xf bound_ctrl:1
	v_add_f32_dpp v24, v24, v24 quad_perm:[1,0,3,2] row_mask:0xf bank_mask:0xf bound_ctrl:1
	v_pk_fma_f32 v[14:15], v[46:47], v[68:69], v[14:15] op_sel_hi:[1,0,1]
	v_pk_fma_f32 v[16:17], v[48:49], v[68:69], v[16:17] op_sel_hi:[1,0,1]
	v_add_f32_dpp v26, v26, v26 quad_perm:[2,3,0,1] row_mask:0xf bank_mask:0xf bound_ctrl:1
	v_add_f32_dpp v24, v24, v24 quad_perm:[2,3,0,1] row_mask:0xf bank_mask:0xf bound_ctrl:1
	v_pk_fma_f32 v[18:19], v[50:51], v[68:69], v[18:19] op_sel_hi:[1,0,1]
	v_add_f32_dpp v26, v26, v26 row_half_mirror row_mask:0xf bank_mask:0xf bound_ctrl:1
	v_add_f32_dpp v24, v24, v24 row_half_mirror row_mask:0xf bank_mask:0xf bound_ctrl:1
	ds_write_b32 v76, v26 offset:3200
	v_pk_fma_f32 v[8:9], v[60:61], v[24:25], v[12:13] op_sel_hi:[1,0,1]
	v_pk_fma_f32 v[10:11], v[62:63], v[24:25], v[14:15] op_sel_hi:[1,0,1]
	v_pk_fma_f32 v[20:21], v[64:65], v[24:25], v[16:17] op_sel_hi:[1,0,1]
	v_pk_fma_f32 v[22:23], v[66:67], v[24:25], v[18:19] op_sel_hi:[1,0,1]
	v_pk_mul_f32 v[4:5], v[8:9], v[28:29]
	v_pk_mul_f32 v[6:7], v[10:11], v[30:31]
	v_pk_fma_f32 v[4:5], v[20:21], v[32:33], v[4:5]
	v_pk_fma_f32 v[6:7], v[22:23], v[34:35], v[6:7]
	ds_read_b128 v[52:55], v74 offset:31744
	ds_read_b128 v[56:59], v74 offset:31760
	ds_read_b128 v[36:39], v74 offset:15360
	ds_read_b128 v[40:43], v74 offset:15376
	ds_read_b128 v[44:47], v74 offset:23552
	ds_read_b128 v[48:51], v74 offset:23568
	ds_read_b128 v[60:63], v74 offset:39936
	ds_read_b128 v[64:67], v74 offset:39952
	ds_read_b128 v[28:31], v74 offset:7168
	ds_read_b128 v[32:35], v74 offset:7184
	ds_read_b32 v68, v75 offset:44544
	s_waitcnt lgkmcnt(12)
	v_pk_mul_f32 v[0:1], v[8:9], v[130:131]
	v_pk_mul_f32 v[2:3], v[10:11], v[132:133]
	v_pk_fma_f32 v[0:1], v[20:21], v[134:135], v[0:1]
	v_pk_fma_f32 v[2:3], v[22:23], v[136:137], v[2:3]
	v_pk_add_f32 v[4:5], v[4:5], v[6:7]
	v_pk_mul_f32 v[12:13], v[8:9], v[114:115]
	v_pk_add_f32 v[0:1], v[0:1], v[2:3]
	v_pk_mul_f32 v[14:15], v[10:11], v[116:117]
	v_add_f32_e32 v26, v4, v5
	v_pk_mul_f32 v[16:17], v[20:21], v[118:119]
	v_add_f32_e32 v24, v0, v1
	v_pk_mul_f32 v[18:19], v[22:23], v[120:121]
	v_pk_fma_f32 v[12:13], v[122:123], v[72:73], v[12:13] op_sel_hi:[1,0,1]
	v_add_f32_dpp v26, v26, v26 quad_perm:[1,0,3,2] row_mask:0xf bank_mask:0xf bound_ctrl:1
	v_add_f32_dpp v24, v24, v24 quad_perm:[1,0,3,2] row_mask:0xf bank_mask:0xf bound_ctrl:1
	v_pk_fma_f32 v[14:15], v[124:125], v[72:73], v[14:15] op_sel_hi:[1,0,1]
	v_pk_fma_f32 v[16:17], v[126:127], v[72:73], v[16:17] op_sel_hi:[1,0,1]
	v_add_f32_dpp v26, v26, v26 quad_perm:[2,3,0,1] row_mask:0xf bank_mask:0xf bound_ctrl:1
	v_add_f32_dpp v24, v24, v24 quad_perm:[2,3,0,1] row_mask:0xf bank_mask:0xf bound_ctrl:1
	v_pk_fma_f32 v[18:19], v[128:129], v[72:73], v[18:19] op_sel_hi:[1,0,1]
	v_add_f32_dpp v26, v26, v26 row_half_mirror row_mask:0xf bank_mask:0xf bound_ctrl:1
	v_add_f32_dpp v24, v24, v24 row_half_mirror row_mask:0xf bank_mask:0xf bound_ctrl:1
	ds_write_b32 v76, v26 offset:3328
	v_pk_fma_f32 v[8:9], v[138:139], v[24:25], v[12:13] op_sel_hi:[1,0,1]
	v_pk_fma_f32 v[10:11], v[140:141], v[24:25], v[14:15] op_sel_hi:[1,0,1]
	v_pk_fma_f32 v[20:21], v[142:143], v[24:25], v[16:17] op_sel_hi:[1,0,1]
	v_pk_fma_f32 v[22:23], v[144:145], v[24:25], v[18:19] op_sel_hi:[1,0,1]
	v_pk_mul_f32 v[4:5], v[8:9], v[106:107]
	v_pk_mul_f32 v[6:7], v[10:11], v[108:109]
	v_pk_fma_f32 v[4:5], v[20:21], v[110:111], v[4:5]
	v_pk_fma_f32 v[6:7], v[22:23], v[112:113], v[6:7]
	ds_read_b128 v[130:133], v74 offset:32000
	ds_read_b128 v[134:137], v74 offset:32016
	ds_read_b128 v[114:117], v74 offset:15616
	ds_read_b128 v[118:121], v74 offset:15632
	ds_read_b128 v[122:125], v74 offset:23808
	ds_read_b128 v[126:129], v74 offset:23824
	ds_read_b128 v[138:141], v74 offset:40192
	ds_read_b128 v[142:145], v74 offset:40208
	ds_read_b128 v[106:109], v74 offset:7424
	ds_read_b128 v[110:113], v74 offset:7440
	ds_read_b32 v72, v75 offset:44672
	s_waitcnt lgkmcnt(12)
; __device__ __forceinline__ void rwkv_scan_phase(Frame& F, const bf16* RKV, const float* WAG, const bf16* AGB, const float* k_k, const float* k_a, const float* r_k, bf16* Y, float* BS, float* ST2) {
;     ...
;                 f32x2 r0[4], w0[4], k0[4], a0[4], b0[4], r1[4], w1[4], k1[4], a1[4], b1[4]; float v0, v1;
;                 SC_LOAD(r0, w0, k0, a0, b0, v0, 0);
; #pragma unroll
;                 for (int t = 0; t < SC_T; t += 2) {
;                     SC_LOAD(r1, w1, k1, a1, b1, v1, t + 1);
;                     SC_STEP(r0, w0, k0, a0, b0, v0, t);
;                     if (t + 2 < SC_T) SC_LOAD(r0, w0, k0, a0, b0, v0, t + 2);
;                     SC_STEP(r1, w1, k1, a1, b1, v1, t + 1);
;                 }
	v_pk_mul_f32 v[0:1], v[8:9], v[52:53]
	v_pk_mul_f32 v[2:3], v[10:11], v[54:55]
	v_pk_fma_f32 v[0:1], v[20:21], v[56:57], v[0:1]
	v_pk_fma_f32 v[2:3], v[22:23], v[58:59], v[2:3]
	v_pk_add_f32 v[4:5], v[4:5], v[6:7]
	v_pk_mul_f32 v[12:13], v[8:9], v[36:37]
	v_pk_add_f32 v[0:1], v[0:1], v[2:3]
	v_pk_mul_f32 v[14:15], v[10:11], v[38:39]
	v_add_f32_e32 v26, v4, v5
	v_pk_mul_f32 v[16:17], v[20:21], v[40:41]
	v_add_f32_e32 v24, v0, v1
	v_pk_mul_f32 v[18:19], v[22:23], v[42:43]
	v_pk_fma_f32 v[12:13], v[44:45], v[68:69], v[12:13] op_sel_hi:[1,0,1]
	v_add_f32_dpp v26, v26, v26 quad_perm:[1,0,3,2] row_mask:0xf bank_mask:0xf bound_ctrl:1
	v_add_f32_dpp v24, v24, v24 quad_perm:[1,0,3,2] row_mask:0xf bank_mask:0xf bound_ctrl:1
	v_pk_fma_f32 v[14:15], v[46:47], v[68:69], v[14:15] op_sel_hi:[1,0,1]
	v_pk_fma_f32 v[16:17], v[48:49], v[68:69], v[16:17] op_sel_hi:[1,0,1]
	v_add_f32_dpp v26, v26, v26 quad_perm:[2,3,0,1] row_mask:0xf bank_mask:0xf bound_ctrl:1
	v_add_f32_dpp v24, v24, v24 quad_perm:[2,3,0,1] row_mask:0xf bank_mask:0xf bound_ctrl:1
	v_pk_fma_f32 v[18:19], v[50:51], v[68:69], v[18:19] op_sel_hi:[1,0,1]
	v_add_f32_dpp v26, v26, v26 row_half_mirror row_mask:0xf bank_mask:0xf bound_ctrl:1
	v_add_f32_dpp v24, v24, v24 row_half_mirror row_mask:0xf bank_mask:0xf bound_ctrl:1
	ds_write_b32 v76, v26 offset:3456
	v_pk_fma_f32 v[8:9], v[60:61], v[24:25], v[12:13] op_sel_hi:[1,0,1]
	v_pk_fma_f32 v[10:11], v[62:63], v[24:25], v[14:15] op_sel_hi:[1,0,1]
	v_pk_fma_f32 v[20:21], v[64:65], v[24:25], v[16:17] op_sel_hi:[1,0,1]
	v_pk_fma_f32 v[22:23], v[66:67], v[24:25], v[18:19] op_sel_hi:[1,0,1]
	v_pk_mul_f32 v[4:5], v[8:9], v[28:29]
	v_pk_mul_f32 v[6:7], v[10:11], v[30:31]
	v_pk_fma_f32 v[4:5], v[20:21], v[32:33], v[4:5]
	v_pk_fma_f32 v[6:7], v[22:23], v[34:35], v[6:7]
	ds_read_b128 v[52:55], v74 offset:32256
	ds_read_b128 v[56:59], v74 offset:32272
	ds_read_b128 v[36:39], v74 offset:15872
	ds_read_b128 v[40:43], v74 offset:15888
	ds_read_b128 v[44:47], v74 offset:24064
	ds_read_b128 v[48:51], v74 offset:24080
	ds_read_b128 v[60:63], v74 offset:40448
	ds_read_b128 v[64:67], v74 offset:40464
	ds_read_b128 v[28:31], v74 offset:7680
	ds_read_b128 v[32:35], v74 offset:7696
	ds_read_b32 v68, v75 offset:44800
	s_waitcnt lgkmcnt(12)
	v_pk_mul_f32 v[0:1], v[8:9], v[130:131]
	v_pk_mul_f32 v[2:3], v[10:11], v[132:133]
	v_pk_fma_f32 v[0:1], v[20:21], v[134:135], v[0:1]
	v_pk_fma_f32 v[2:3], v[22:23], v[136:137], v[2:3]
	v_pk_add_f32 v[4:5], v[4:5], v[6:7]
	v_pk_mul_f32 v[12:13], v[8:9], v[114:115]
	v_pk_add_f32 v[0:1], v[0:1], v[2:3]
	v_pk_mul_f32 v[14:15], v[10:11], v[116:117]
	v_add_f32_e32 v26, v4, v5
	v_pk_mul_f32 v[16:17], v[20:21], v[118:119]
	v_add_f32_e32 v24, v0, v1
	v_pk_mul_f32 v[18:19], v[22:23], v[120:121]
	v_pk_fma_f32 v[12:13], v[122:123], v[72:73], v[12:13] op_sel_hi:[1,0,1]
	v_add_f32_dpp v26, v26, v26 quad_perm:[1,0,3,2] row_mask:0xf bank_mask:0xf bound_ctrl:1
	v_add_f32_dpp v24, v24, v24 quad_perm:[1,0,3,2] row_mask:0xf bank_mask:0xf bound_ctrl:1
	v_pk_fma_f32 v[14:15], v[124:125], v[72:73], v[14:15] op_sel_hi:[1,0,1]
	v_pk_fma_f32 v[16:17], v[126:127], v[72:73], v[16:17] op_sel_hi:[1,0,1]
	v_add_f32_dpp v26, v26, v26 quad_perm:[2,3,0,1] row_mask:0xf bank_mask:0xf bound_ctrl:1
	v_add_f32_dpp v24, v24, v24 quad_perm:[2,3,0,1] row_mask:0xf bank_mask:0xf bound_ctrl:1
	v_pk_fma_f32 v[18:19], v[128:129], v[72:73], v[18:19] op_sel_hi:[1,0,1]
	v_add_f32_dpp v26, v26, v26 row_half_mirror row_mask:0xf bank_mask:0xf bound_ctrl:1
	v_add_f32_dpp v24, v24, v24 row_half_mirror row_mask:0xf bank_mask:0xf bound_ctrl:1
	ds_write_b32 v76, v26 offset:3584
	v_pk_fma_f32 v[8:9], v[138:139], v[24:25], v[12:13] op_sel_hi:[1,0,1]
	v_pk_fma_f32 v[10:11], v[140:141], v[24:25], v[14:15] op_sel_hi:[1,0,1]
	v_pk_fma_f32 v[20:21], v[142:143], v[24:25], v[16:17] op_sel_hi:[1,0,1]
	v_pk_fma_f32 v[22:23], v[144:145], v[24:25], v[18:19] op_sel_hi:[1,0,1]
	v_pk_mul_f32 v[4:5], v[8:9], v[106:107]
	v_pk_mul_f32 v[6:7], v[10:11], v[108:109]
	v_pk_fma_f32 v[4:5], v[20:21], v[110:111], v[4:5]
	v_pk_fma_f32 v[6:7], v[22:23], v[112:113], v[6:7]
	ds_read_b128 v[130:133], v74 offset:32512
	ds_read_b128 v[134:137], v74 offset:32528
	ds_read_b128 v[114:117], v74 offset:16128
	ds_read_b128 v[118:121], v74 offset:16144
	ds_read_b128 v[122:125], v74 offset:24320
	ds_read_b128 v[126:129], v74 offset:24336
	ds_read_b128 v[138:141], v74 offset:40704
	ds_read_b128 v[142:145], v74 offset:40720
	ds_read_b128 v[106:109], v74 offset:7936
	ds_read_b128 v[110:113], v74 offset:7952
	ds_read_b32 v72, v75 offset:44928
	s_waitcnt lgkmcnt(12)
; __device__ __forceinline__ void rwkv_scan_phase(Frame& F, const bf16* RKV, const float* WAG, const bf16* AGB, const float* k_k, const float* k_a, const float* r_k, bf16* Y, float* BS, float* ST2) {
;     ...
;                 f32x2 r0[4], w0[4], k0[4], a0[4], b0[4], r1[4], w1[4], k1[4], a1[4], b1[4]; float v0, v1;
;                 SC_LOAD(r0, w0, k0, a0, b0, v0, 0);
; #pragma unroll
;                 for (int t = 0; t < SC_T; t += 2) {
;                     SC_LOAD(r1, w1, k1, a1, b1, v1, t + 1);
;                     SC_STEP(r0, w0, k0, a0, b0, v0, t);
;                     if (t + 2 < SC_T) SC_LOAD(r0, w0, k0, a0, b0, v0, t + 2);
;                     SC_STEP(r1, w1, k1, a1, b1, v1, t + 1);
;                 }
	v_pk_mul_f32 v[0:1], v[8:9], v[52:53]
	v_pk_mul_f32 v[2:3], v[10:11], v[54:55]
	v_pk_fma_f32 v[0:1], v[20:21], v[56:57], v[0:1]
	v_pk_fma_f32 v[2:3], v[22:23], v[58:59], v[2:3]
	v_pk_add_f32 v[4:5], v[4:5], v[6:7]
	v_pk_mul_f32 v[12:13], v[8:9], v[36:37]
	v_pk_add_f32 v[0:1], v[0:1], v[2:3]
	v_pk_mul_f32 v[14:15], v[10:11], v[38:39]
	v_add_f32_e32 v26, v4, v5
	v_pk_mul_f32 v[16:17], v[20:21], v[40:41]
	v_add_f32_e32 v24, v0, v1
	v_pk_mul_f32 v[18:19], v[22:23], v[42:43]
	v_pk_fma_f32 v[12:13], v[44:45], v[68:69], v[12:13] op_sel_hi:[1,0,1]
	v_add_f32_dpp v26, v26, v26 quad_perm:[1,0,3,2] row_mask:0xf bank_mask:0xf bound_ctrl:1
	v_add_f32_dpp v24, v24, v24 quad_perm:[1,0,3,2] row_mask:0xf bank_mask:0xf bound_ctrl:1
	v_pk_fma_f32 v[14:15], v[46:47], v[68:69], v[14:15] op_sel_hi:[1,0,1]
	v_pk_fma_f32 v[16:17], v[48:49], v[68:69], v[16:17] op_sel_hi:[1,0,1]
	v_add_f32_dpp v26, v26, v26 quad_perm:[2,3,0,1] row_mask:0xf bank_mask:0xf bound_ctrl:1
	v_add_f32_dpp v24, v24, v24 quad_perm:[2,3,0,1] row_mask:0xf bank_mask:0xf bound_ctrl:1
	v_pk_fma_f32 v[18:19], v[50:51], v[68:69], v[18:19] op_sel_hi:[1,0,1]
	v_add_f32_dpp v26, v26, v26 row_half_mirror row_mask:0xf bank_mask:0xf bound_ctrl:1
	v_add_f32_dpp v24, v24, v24 row_half_mirror row_mask:0xf bank_mask:0xf bound_ctrl:1
	ds_write_b32 v76, v26 offset:3712
	v_pk_fma_f32 v[8:9], v[60:61], v[24:25], v[12:13] op_sel_hi:[1,0,1]
	v_pk_fma_f32 v[10:11], v[62:63], v[24:25], v[14:15] op_sel_hi:[1,0,1]
	v_pk_fma_f32 v[20:21], v[64:65], v[24:25], v[16:17] op_sel_hi:[1,0,1]
	v_pk_fma_f32 v[22:23], v[66:67], v[24:25], v[18:19] op_sel_hi:[1,0,1]
	v_pk_mul_f32 v[4:5], v[8:9], v[28:29]
	v_pk_mul_f32 v[6:7], v[10:11], v[30:31]
	v_pk_fma_f32 v[4:5], v[20:21], v[32:33], v[4:5]
	v_pk_fma_f32 v[6:7], v[22:23], v[34:35], v[6:7]
	s_waitcnt lgkmcnt(1)
	v_pk_mul_f32 v[0:1], v[8:9], v[130:131]
	v_pk_mul_f32 v[2:3], v[10:11], v[132:133]
	v_pk_fma_f32 v[0:1], v[20:21], v[134:135], v[0:1]
	v_pk_fma_f32 v[2:3], v[22:23], v[136:137], v[2:3]
	v_pk_add_f32 v[4:5], v[4:5], v[6:7]
	v_pk_mul_f32 v[12:13], v[8:9], v[114:115]
	v_pk_add_f32 v[0:1], v[0:1], v[2:3]
	v_pk_mul_f32 v[14:15], v[10:11], v[116:117]
	v_add_f32_e32 v26, v4, v5
	v_pk_mul_f32 v[16:17], v[20:21], v[118:119]
	v_add_f32_e32 v24, v0, v1
	v_pk_mul_f32 v[18:19], v[22:23], v[120:121]
	v_pk_fma_f32 v[12:13], v[122:123], v[72:73], v[12:13] op_sel_hi:[1,0,1]
	v_add_f32_dpp v26, v26, v26 quad_perm:[1,0,3,2] row_mask:0xf bank_mask:0xf bound_ctrl:1
	v_add_f32_dpp v24, v24, v24 quad_perm:[1,0,3,2] row_mask:0xf bank_mask:0xf bound_ctrl:1
	v_pk_fma_f32 v[14:15], v[124:125], v[72:73], v[14:15] op_sel_hi:[1,0,1]
	v_pk_fma_f32 v[16:17], v[126:127], v[72:73], v[16:17] op_sel_hi:[1,0,1]
	v_add_f32_dpp v26, v26, v26 quad_perm:[2,3,0,1] row_mask:0xf bank_mask:0xf bound_ctrl:1
	v_add_f32_dpp v24, v24, v24 quad_perm:[2,3,0,1] row_mask:0xf bank_mask:0xf bound_ctrl:1
	v_pk_fma_f32 v[18:19], v[128:129], v[72:73], v[18:19] op_sel_hi:[1,0,1]
	v_add_f32_dpp v26, v26, v26 row_half_mirror row_mask:0xf bank_mask:0xf bound_ctrl:1
	v_add_f32_dpp v24, v24, v24 row_half_mirror row_mask:0xf bank_mask:0xf bound_ctrl:1
	ds_write_b32 v76, v26 offset:3840
	v_pk_fma_f32 v[8:9], v[138:139], v[24:25], v[12:13] op_sel_hi:[1,0,1]
	v_pk_fma_f32 v[10:11], v[140:141], v[24:25], v[14:15] op_sel_hi:[1,0,1]
	v_pk_fma_f32 v[20:21], v[142:143], v[24:25], v[16:17] op_sel_hi:[1,0,1]
	v_pk_fma_f32 v[22:23], v[144:145], v[24:25], v[18:19] op_sel_hi:[1,0,1]
	v_pk_mul_f32 v[4:5], v[8:9], v[106:107]
	v_pk_mul_f32 v[6:7], v[10:11], v[108:109]
	v_pk_fma_f32 v[4:5], v[20:21], v[110:111], v[4:5]
	v_pk_fma_f32 v[6:7], v[22:23], v[112:113], v[6:7]
	v_pk_add_f32 v[4:5], v[4:5], v[6:7]
	v_add_f32_e32 v26, v4, v5
	s_nop 1
	v_add_f32_dpp v26, v26, v26 quad_perm:[1,0,3,2] row_mask:0xf bank_mask:0xf bound_ctrl:1
	s_nop 1
	v_add_f32_dpp v26, v26, v26 quad_perm:[2,3,0,1] row_mask:0xf bank_mask:0xf bound_ctrl:1
	s_nop 1
	v_add_f32_dpp v26, v26, v26 row_half_mirror row_mask:0xf bank_mask:0xf bound_ctrl:1
	ds_write_b32 v76, v26 offset:3968
	s_mov_b64 s[6:7], 0
	s_branch .LBB0_1691
